# sample attention P.V loop unrolled over the page's four V tiles; six of the next tile's sixteen loads issued one tile early into registers dead in that loop (22 loads in flight instead of 16)
# baseline (speedup 1.0000x reference)
.LBB0_1610:
	s_add_i32 s42, s1, s40
	s_add_i32 s52, s42, s41
	s_ashr_i32 s53, s52, 31
	s_lshl_b64 s[52:53], s[52:53], 2
	s_add_u32 s52, s50, s52
	s_addc_u32 s53, s51, s53
	s_cmp_lg_u32 s1, 0
	s_cbranch_scc1 .Lpt_have
	global_load_dword v254, v137, s[52:53]
.Lpt_have:
	s_cmp_lt_u32 s1, 3
	s_cselect_b32 s32, 4, 0
	s_add_u32 s90, s52, s32
	s_addc_u32 s91, s53, 0
	v_mov_b32_e32 v145, v48
	v_mov_b32_e32 v144, v49
	v_mov_b32_e32 v143, v50
	v_mov_b32_e32 v142, v51
	v_add_u32_e32 v146, 0x800, v203
	s_waitcnt vmcnt(0)
	v_readfirstlane_b32 s52, v254
	global_load_dword v254, v137, s[90:91]
	s_ashr_i32 s53, s52, 31
	s_lshl_b64 s[54:55], s[52:53], 17
	s_add_u32 s54, s54, s10
	s_addc_u32 s55, s55, s11
	s_lshl_b64 s[54:55], s[54:55], 2
	s_add_u32 s88, s4, s54
	s_addc_u32 s89, s5, s55
	v_lshl_add_u64 v[112:113], s[88:89], 0, v[136:137]
	v_add_co_u32_e32 v48, vcc, s44, v112
	s_lshl_b32 s48, s42, 7
	s_nop 0
	v_addc_co_u32_e32 v49, vcc, 0, v113, vcc
	v_add_co_u32_e32 v50, vcc, s49, v112
	v_or_b32_e32 v86, s48, v180
	s_nop 0
	v_addc_co_u32_e32 v51, vcc, 0, v113, vcc
	v_add_co_u32_e32 v52, vcc, s56, v112
	global_load_dwordx4 v[76:79], v[112:113], off nt
	global_load_dwordx4 v[68:71], v[48:49], off nt
	global_load_dwordx4 v[60:63], v[50:51], off nt
	v_addc_co_u32_e32 v53, vcc, 0, v113, vcc
	v_add_co_u32_e32 v54, vcc, s57, v112
	v_sub_u32_e32 v150, v198, v86
	s_nop 0
	v_addc_co_u32_e32 v55, vcc, 0, v113, vcc
	v_add_co_u32_e32 v56, vcc, s58, v112
	v_sub_u32_e32 v151, v199, v86
	s_nop 0
	v_addc_co_u32_e32 v57, vcc, 0, v113, vcc
	v_add_co_u32_e32 v58, vcc, s59, v112
	v_sub_u32_e32 v149, v200, v86
	s_nop 0
	v_addc_co_u32_e32 v59, vcc, 0, v113, vcc
	v_add_co_u32_e32 v84, vcc, s60, v112
	global_load_dwordx4 v[72:75], v[52:53], off nt
	global_load_dwordx4 v[64:67], v[54:55], off nt
	s_nop 0
	global_load_dwordx4 v[52:55], v[56:57], off nt
	global_load_dwordx4 v[48:51], v[58:59], off nt
	v_addc_co_u32_e32 v85, vcc, 0, v113, vcc
	global_load_dwordx4 v[56:59], v[84:85], off nt
	v_add_co_u32_e32 v80, vcc, s61, v112
	v_sub_u32_e32 v148, v201, v86
	s_nop 0
	v_addc_co_u32_e32 v81, vcc, 0, v113, vcc
	v_add_co_u32_e32 v82, vcc, s62, v112
	s_mov_b32 s42, 0x20000
	s_nop 0
	v_addc_co_u32_e32 v83, vcc, 0, v113, vcc
	v_add_co_u32_e32 v98, vcc, s63, v112
	v_cvt_f32_i32_e32 v150, v150
	s_nop 0
	v_addc_co_u32_e32 v99, vcc, 0, v113, vcc
	v_add_co_u32_e32 v92, vcc, s64, v112
	global_load_dwordx4 v[88:91], v[80:81], off nt
	global_load_dwordx4 v[84:87], v[82:83], off nt
	s_nop 0
	global_load_dwordx4 v[80:83], v[98:99], off nt
	v_addc_co_u32_e32 v93, vcc, 0, v113, vcc
	v_add_co_u32_e32 v94, vcc, s65, v112
	global_load_dwordx4 v[104:107], v[92:93], off nt
	s_nop 0
	v_addc_co_u32_e32 v95, vcc, 0, v113, vcc
	v_add_co_u32_e32 v96, vcc, s66, v112
	v_cvt_f32_i32_e32 v151, v151
	s_nop 0
	v_addc_co_u32_e32 v97, vcc, 0, v113, vcc
	v_add_co_u32_e32 v114, vcc, s67, v112
	v_cvt_f32_i32_e32 v149, v149
	s_nop 0
	v_addc_co_u32_e32 v115, vcc, 0, v113, vcc
	v_add_co_u32_e32 v130, vcc, s68, v112
	v_cvt_f32_i32_e32 v148, v148
	s_nop 0
	v_addc_co_u32_e32 v131, vcc, 0, v113, vcc
	global_load_dwordx4 v[108:111], v[94:95], off nt
	global_load_dwordx4 v[100:103], v[96:97], off nt
	s_nop 0
	global_load_dwordx4 v[96:99], v[114:115], off nt
	global_load_dwordx4 v[92:95], v[130:131], off nt
	v_add_co_u32_e32 v152, vcc, s42, v112
	s_mov_b32 s42, 0x22000
	s_nop 0
	v_addc_co_u32_e32 v153, vcc, 0, v113, vcc
	v_add_co_u32_e32 v154, vcc, s42, v112
	s_mov_b32 s42, 0x24000
	s_nop 0
	v_addc_co_u32_e32 v155, vcc, 0, v113, vcc
	v_add_co_u32_e32 v156, vcc, s42, v112
	s_mov_b32 s42, 0x26000
	s_nop 0
	v_addc_co_u32_e32 v157, vcc, 0, v113, vcc
	v_add_co_u32_e32 v132, vcc, s42, v112
	s_mov_b32 s42, 0x28000
	s_nop 0
	v_addc_co_u32_e32 v133, vcc, 0, v113, vcc
	v_add_co_u32_e32 v158, vcc, s42, v112
	s_waitcnt vmcnt(15)
	v_cvt_pk_bf16_f32 v76, v76, v77
	v_cvt_pk_bf16_f32 v77, v78, v79
	s_waitcnt vmcnt(14)
	v_cvt_pk_bf16_f32 v68, v68, v69
	v_cvt_pk_bf16_f32 v69, v70, v71
	v_addc_co_u32_e32 v159, vcc, 0, v113, vcc
	s_mov_b32 s42, 0x2a000
	s_waitcnt vmcnt(13)
	v_cvt_pk_bf16_f32 v60, v60, v61
	v_cvt_pk_bf16_f32 v61, v62, v63
	v_add_co_u32_e32 v134, vcc, s42, v112
	s_waitcnt vmcnt(12)
	v_cvt_pk_bf16_f32 v62, v72, v73
	v_cvt_pk_bf16_f32 v63, v74, v75
	s_waitcnt vmcnt(11)
	v_cvt_pk_bf16_f32 v64, v64, v65
	v_cvt_pk_bf16_f32 v65, v66, v67
	s_waitcnt vmcnt(10)
	v_cvt_pk_bf16_f32 v52, v52, v53
	v_cvt_pk_bf16_f32 v53, v54, v55
	s_waitcnt vmcnt(9)
	v_cvt_pk_bf16_f32 v48, v48, v49
	v_cvt_pk_bf16_f32 v49, v50, v51
	s_waitcnt vmcnt(8)
	v_cvt_pk_bf16_f32 v50, v56, v57
	v_cvt_pk_bf16_f32 v51, v58, v59
	ds_write2_b64 v203, v[76:77], v[68:69] offset1:68
	ds_write2_b64 v203, v[60:61], v[62:63] offset0:136 offset1:204
	ds_write2_b64 v146, v[64:65], v[52:53] offset0:16 offset1:84
	ds_write2_b64 v146, v[48:49], v[50:51] offset0:152 offset1:220
	s_waitcnt lgkmcnt(0)
	v_addc_co_u32_e32 v135, vcc, 0, v113, vcc
	s_mov_b32 s42, 0x2c000
	v_add_co_u32_e32 v160, vcc, s42, v112
	ds_read_b128 v[52:55], v204
	ds_read_b128 v[56:59], v204 offset:64
	ds_read_b128 v[60:63], v204 offset:128
	ds_read_b128 v[64:67], v204 offset:192
	s_waitcnt lgkmcnt(0)
	v_addc_co_u32_e32 v161, vcc, 0, v113, vcc
	s_mov_b32 s42, 0x2e000
	v_add_co_u32_e32 v164, vcc, s42, v112
	global_load_dwordx4 v[68:71], v[152:153], off nt
	global_load_dwordx4 v[72:75], v[154:155], off nt
	global_load_dwordx4 v[48:51], v[156:157], off nt
	v_addc_co_u32_e32 v165, vcc, 0, v113, vcc
	global_load_dwordx4 v[76:79], v[132:133], off nt
	global_load_dwordx4 v[152:155], v[158:159], off nt
	s_nop 0
	global_load_dwordx4 v[156:159], v[134:135], off nt
	s_nop 0
	global_load_dwordx4 v[160:163], v[160:161], off nt
	s_nop 0
	global_load_dwordx4 v[164:167], v[164:165], off nt
	s_mov_b32 s42, 0x30000
	v_add_co_u32_e32 v114, vcc, s42, v112
	s_mov_b32 s42, 0x32000
	s_nop 0
	v_addc_co_u32_e32 v115, vcc, 0, v113, vcc
	v_add_co_u32_e32 v130, vcc, s42, v112
	s_waitcnt vmcnt(15)
	v_cvt_pk_bf16_f32 v88, v88, v89
	v_cvt_pk_bf16_f32 v89, v90, v91
	s_waitcnt vmcnt(14)
	v_cvt_pk_bf16_f32 v84, v84, v85
	v_cvt_pk_bf16_f32 v85, v86, v87
	v_addc_co_u32_e32 v131, vcc, 0, v113, vcc
	s_mov_b32 s42, 0x34000
	s_waitcnt vmcnt(13)
	v_cvt_pk_bf16_f32 v80, v80, v81
	v_cvt_pk_bf16_f32 v81, v82, v83
	s_waitcnt vmcnt(12)
	v_cvt_pk_bf16_f32 v82, v104, v105
	v_cvt_pk_bf16_f32 v83, v106, v107
	s_waitcnt vmcnt(11)
	v_cvt_pk_bf16_f32 v86, v108, v109
	v_cvt_pk_bf16_f32 v87, v110, v111
	s_waitcnt vmcnt(10)
	v_cvt_pk_bf16_f32 v90, v100, v101
	v_cvt_pk_bf16_f32 v91, v102, v103
	s_waitcnt vmcnt(9)
	v_cvt_pk_bf16_f32 v96, v96, v97
	v_cvt_pk_bf16_f32 v97, v98, v99
	s_waitcnt vmcnt(8)
	v_cvt_pk_bf16_f32 v92, v92, v93
	v_cvt_pk_bf16_f32 v93, v94, v95
	ds_write2_b64 v203, v[88:89], v[84:85] offset1:68
	ds_write2_b64 v203, v[80:81], v[82:83] offset0:136 offset1:204
	ds_write2_b64 v146, v[86:87], v[90:91] offset0:16 offset1:84
	ds_write2_b64 v146, v[96:97], v[92:93] offset0:152 offset1:220
	s_waitcnt lgkmcnt(7)
	v_mfma_f32_16x16x32_bf16 v[52:55], v[4:7], v[52:55], 0
	v_add_co_u32_e32 v140, vcc, s42, v112
	s_waitcnt lgkmcnt(0)
	s_mov_b32 s42, 0x36000
	s_nop 0
	v_addc_co_u32_e32 v141, vcc, 0, v113, vcc
	v_add_co_u32_e32 v168, vcc, s42, v112
	ds_read_b128 v[80:83], v204
	s_nop 0
	v_addc_co_u32_e32 v169, vcc, 0, v113, vcc
	s_mov_b32 s42, 0x38000
	s_waitcnt lgkmcnt(7)
	v_mfma_f32_16x16x32_bf16 v[52:55], v[0:3], v[56:59], v[52:55]
	v_add_co_u32_e32 v132, vcc, s42, v112
	s_mov_b32 s42, 0x3a000
	s_nop 0
	v_addc_co_u32_e32 v133, vcc, 0, v113, vcc
	v_add_co_u32_e32 v134, vcc, s42, v112
	ds_read_b128 v[56:59], v204 offset:64
	s_nop 0
	v_addc_co_u32_e32 v135, vcc, 0, v113, vcc
	s_mov_b32 s42, 0x3c000
	s_waitcnt lgkmcnt(1)
	v_mfma_f32_16x16x32_bf16 v[80:83], v[4:7], v[80:83], 0
	v_add_co_u32_e32 v170, vcc, s42, v112
	s_mov_b32 s42, 0x3e000
	v_mfma_f32_16x16x32_bf16 v[52:55], v[12:15], v[60:63], v[52:55]
	v_addc_co_u32_e32 v171, vcc, 0, v113, vcc
	ds_read_b128 v[60:63], v204 offset:128
	ds_read_b128 v[84:87], v204 offset:192
	s_waitcnt lgkmcnt(0)
	v_add_co_u32_e32 v172, vcc, s42, v112
	s_waitcnt lgkmcnt(2)
	v_mfma_f32_16x16x32_bf16 v[56:59], v[0:3], v[56:59], v[80:83]
	v_addc_co_u32_e32 v173, vcc, 0, v113, vcc
	s_nop 1
	global_load_dwordx4 v[80:83], v[114:115], off nt
	global_load_dwordx4 v[88:91], v[130:131], off nt
	global_load_dwordx4 v[92:95], v[140:141], off nt
	global_load_dwordx4 v[96:99], v[168:169], off nt
	v_mfma_f32_16x16x32_bf16 v[52:55], v[8:11], v[64:67], v[52:55]
	global_load_dwordx4 v[64:67], v[132:133], off nt
	global_load_dwordx4 v[100:103], v[134:135], off nt
	global_load_dwordx4 v[104:107], v[170:171], off nt
	global_load_dwordx4 v[108:111], v[172:173], off nt
	v_or_b32_e32 v147, s48, v184
	v_sub_u32_e32 v174, v198, v147
	s_waitcnt lgkmcnt(1)
	v_mfma_f32_16x16x32_bf16 v[56:59], v[12:15], v[60:63], v[56:59]
	s_waitcnt vmcnt(13)
	v_cvt_pk_bf16_f32 v48, v48, v49
	v_cvt_pk_bf16_f32 v49, v50, v51
	s_waitcnt vmcnt(12)
	v_cvt_pk_bf16_f32 v50, v76, v77
	v_cvt_pk_bf16_f32 v51, v78, v79
	ds_write2_b64 v203, v[48:49], v[50:51] offset0:136 offset1:204
	s_waitcnt vmcnt(11)
	v_cvt_pk_bf16_f32 v48, v152, v153
	v_cvt_pk_bf16_f32 v49, v154, v155
	s_waitcnt vmcnt(10)
	v_cvt_pk_bf16_f32 v50, v156, v157
	v_cvt_pk_bf16_f32 v51, v158, v159
	v_fma_f32 v135, -v177, v150, v52
	v_fma_f32 v133, -v177, v151, v53
	v_fma_f32 v130, -v177, v149, v54
	v_fma_f32 v131, -v177, v148, v55
	s_waitcnt lgkmcnt(1)
	v_mfma_f32_16x16x32_bf16 v[52:55], v[8:11], v[84:87], v[56:59]
	ds_write2_b64 v146, v[48:49], v[50:51] offset0:16 offset1:84
	s_waitcnt vmcnt(9)
	v_cvt_pk_bf16_f32 v48, v160, v161
	v_cvt_pk_bf16_f32 v49, v162, v163
	v_cvt_pk_bf16_f32 v56, v68, v69
	v_cvt_pk_bf16_f32 v57, v70, v71
	v_cvt_pk_bf16_f32 v58, v72, v73
	v_cvt_pk_bf16_f32 v59, v74, v75
	s_waitcnt vmcnt(8)
	v_cvt_pk_bf16_f32 v50, v164, v165
	v_cvt_pk_bf16_f32 v51, v166, v167
	ds_write2_b64 v203, v[56:57], v[58:59] offset1:68
	ds_write2_b64 v146, v[48:49], v[50:51] offset0:152 offset1:220
	s_waitcnt lgkmcnt(0)
	ds_read_b128 v[56:59], v204
	ds_read_b128 v[60:63], v204 offset:64
	s_waitcnt lgkmcnt(1)
	v_mfma_f32_16x16x32_bf16 v[56:59], v[4:7], v[56:59], 0
	ds_read_b128 v[68:71], v204 offset:128
	v_cvt_f32_i32_e32 v174, v174
	v_sub_u32_e32 v48, v199, v147
	s_waitcnt lgkmcnt(1)
	v_mfma_f32_16x16x32_bf16 v[56:59], v[0:3], v[60:63], v[56:59]
	v_sub_u32_e32 v50, v200, v147
	v_cvt_f32_i32_e32 v48, v48
	v_cvt_f32_i32_e32 v51, v50
	v_sub_u32_e32 v50, v201, v147
	ds_read_b128 v[60:63], v204 offset:192
	v_fma_f32 v49, -v177, v174, v52
	v_cvt_f32_i32_e32 v52, v50
	s_waitcnt lgkmcnt(1)
	v_mfma_f32_16x16x32_bf16 v[56:59], v[12:15], v[68:71], v[56:59]
	v_fma_f32 v50, -v177, v48, v53
	v_or_b32_e32 v48, s48, v185
	v_fma_f32 v51, -v177, v51, v54
	v_fma_f32 v132, -v177, v52, v55
	s_waitcnt lgkmcnt(0)
	v_mfma_f32_16x16x32_bf16 v[52:55], v[8:11], v[60:63], v[56:59]
	s_mov_b32 s42, 0x40000
	s_waitcnt lgkmcnt(0)
	s_add_u32 s54, s6, s54
	s_addc_u32 s55, s7, s55
	v_sub_u32_e32 v56, v198, v48
	v_cvt_f32_i32_e32 v134, v56
	v_add_co_u32_e32 v56, vcc, s42, v112
	s_mov_b32 s42, 0x42000
	s_nop 0
	v_addc_co_u32_e32 v57, vcc, 0, v113, vcc
	v_add_co_u32_e32 v60, vcc, s42, v112
	s_mov_b32 s42, 0x44000
	s_nop 0
	v_addc_co_u32_e32 v61, vcc, 0, v113, vcc
	v_add_co_u32_e32 v68, vcc, s42, v112
	s_mov_b32 s42, 0x46000
	s_nop 0
	v_addc_co_u32_e32 v69, vcc, 0, v113, vcc
	v_add_co_u32_e32 v72, vcc, s42, v112
	s_mov_b32 s42, 0x48000
	s_nop 0
	v_addc_co_u32_e32 v73, vcc, 0, v113, vcc
	v_add_co_u32_e32 v76, vcc, s42, v112
	s_mov_b32 s42, 0x4a000
	s_nop 0
	v_addc_co_u32_e32 v77, vcc, 0, v113, vcc
	v_add_co_u32_e32 v84, vcc, s42, v112
	s_mov_b32 s42, 0x4c000
	s_nop 0
	v_addc_co_u32_e32 v85, vcc, 0, v113, vcc
	global_load_dwordx4 v[56:59], v[56:57], off nt
	s_nop 0
	global_load_dwordx4 v[60:63], v[60:61], off nt
	v_add_co_u32_e32 v114, vcc, s42, v112
	global_load_dwordx4 v[68:71], v[68:69], off nt
	s_nop 0
	global_load_dwordx4 v[72:75], v[72:73], off nt
	v_addc_co_u32_e32 v115, vcc, 0, v113, vcc
	s_mov_b32 s42, 0x4e000
	global_load_dwordx4 v[76:79], v[76:77], off nt
	s_nop 0
	global_load_dwordx4 v[84:87], v[84:85], off nt
	v_add_co_u32_e32 v140, vcc, s42, v112
	s_waitcnt vmcnt(13)
	v_cvt_pk_bf16_f32 v80, v80, v81
	v_addc_co_u32_e32 v141, vcc, 0, v113, vcc
	global_load_dwordx4 v[148:151], v[114:115], off nt
	global_load_dwordx4 v[152:155], v[140:141], off nt
	v_cvt_pk_bf16_f32 v81, v82, v83
	s_waitcnt vmcnt(14)
	v_cvt_pk_bf16_f32 v82, v88, v89
	v_cvt_pk_bf16_f32 v83, v90, v91
	s_waitcnt vmcnt(11)
	v_cvt_pk_bf16_f32 v64, v64, v65
	v_cvt_pk_bf16_f32 v65, v66, v67
	s_waitcnt vmcnt(10)
	v_cvt_pk_bf16_f32 v66, v100, v101
	v_cvt_pk_bf16_f32 v67, v102, v103
	ds_write2_b64 v203, v[80:81], v[82:83] offset1:68
	v_cvt_pk_bf16_f32 v80, v92, v93
	v_cvt_pk_bf16_f32 v81, v94, v95
	v_cvt_pk_bf16_f32 v82, v96, v97
	v_cvt_pk_bf16_f32 v83, v98, v99
	ds_write2_b64 v146, v[64:65], v[66:67] offset0:16 offset1:84
	s_waitcnt vmcnt(9)
	v_cvt_pk_bf16_f32 v64, v104, v105
	v_cvt_pk_bf16_f32 v65, v106, v107
	s_waitcnt vmcnt(8)
	v_cvt_pk_bf16_f32 v66, v108, v109
	v_cvt_pk_bf16_f32 v67, v110, v111
	ds_write2_b64 v203, v[80:81], v[82:83] offset0:136 offset1:204
	ds_write2_b64 v146, v[64:65], v[66:67] offset0:152 offset1:220
	s_waitcnt lgkmcnt(0)
	ds_read_b128 v[64:67], v204
	ds_read_b128 v[80:83], v204 offset:64
	s_waitcnt lgkmcnt(1)
	v_mfma_f32_16x16x32_bf16 v[64:67], v[4:7], v[64:67], 0
	v_sub_u32_e32 v88, v200, v48
	v_cvt_f32_i32_e32 v92, v88
	ds_read_b128 v[88:91], v204 offset:128
	s_waitcnt lgkmcnt(1)
	v_mfma_f32_16x16x32_bf16 v[64:67], v[0:3], v[80:83], v[64:67]
	v_fma_f32 v147, -v177, v134, v52
	v_sub_u32_e32 v52, v199, v48
	v_sub_u32_e32 v48, v201, v48
	v_cvt_f32_i32_e32 v48, v48
	ds_read_b128 v[80:83], v204 offset:192
	v_cvt_f32_i32_e32 v52, v52
	s_waitcnt lgkmcnt(1)
	v_mfma_f32_16x16x32_bf16 v[64:67], v[12:15], v[88:91], v[64:67]
	v_fma_f32 v134, -v177, v48, v55
	v_or_b32_e32 v48, s48, v186
	v_fma_f32 v141, -v177, v52, v53
	v_fma_f32 v140, -v177, v92, v54
	s_waitcnt lgkmcnt(0)
	v_mfma_f32_16x16x32_bf16 v[52:55], v[8:11], v[80:83], v[64:67]
	s_mov_b32 s42, 0x50000
	s_waitcnt lgkmcnt(0)
	s_lshl_b64 s[52:53], s[52:53], 19
	s_waitcnt vmcnt(7)
	v_cvt_pk_bf16_f32 v56, v56, v57
	v_sub_u32_e32 v64, v198, v48
	v_cvt_f32_i32_e32 v114, v64
	v_add_co_u32_e32 v64, vcc, s42, v112
	s_mov_b32 s42, 0x52000
	s_nop 0
	v_addc_co_u32_e32 v65, vcc, 0, v113, vcc
	v_add_co_u32_e32 v80, vcc, s42, v112
	s_mov_b32 s42, 0x54000
	s_nop 0
	v_addc_co_u32_e32 v81, vcc, 0, v113, vcc
	v_add_co_u32_e32 v88, vcc, s42, v112
	s_mov_b32 s42, 0x56000
	s_nop 0
	v_addc_co_u32_e32 v89, vcc, 0, v113, vcc
	v_add_co_u32_e32 v92, vcc, s42, v112
	s_mov_b32 s42, 0x58000
	s_nop 0
	v_addc_co_u32_e32 v93, vcc, 0, v113, vcc
	v_add_co_u32_e32 v96, vcc, s42, v112
	global_load_dwordx4 v[64:67], v[64:65], off nt
	s_nop 0
	global_load_dwordx4 v[80:83], v[80:81], off nt
	v_addc_co_u32_e32 v97, vcc, 0, v113, vcc
	s_mov_b32 s42, 0x5a000
	global_load_dwordx4 v[88:91], v[88:89], off nt
	s_nop 0
	global_load_dwordx4 v[92:95], v[92:93], off nt
	v_add_co_u32_e32 v100, vcc, s42, v112
	s_mov_b32 s42, 0x5c000
	s_nop 0
	v_addc_co_u32_e32 v101, vcc, 0, v113, vcc
	global_load_dwordx4 v[96:99], v[96:97], off nt
	s_nop 0
	global_load_dwordx4 v[100:103], v[100:101], off nt
	v_add_co_u32_e32 v104, vcc, s42, v112
	s_mov_b32 s42, 0x5e000
	s_nop 0
	v_addc_co_u32_e32 v105, vcc, 0, v113, vcc
	v_add_co_u32_e32 v108, vcc, s42, v112
	v_cvt_pk_bf16_f32 v57, v58, v59
	s_nop 0
	v_addc_co_u32_e32 v109, vcc, 0, v113, vcc
	global_load_dwordx4 v[104:107], v[104:105], off nt
	s_nop 0
	global_load_dwordx4 v[108:111], v[108:109], off nt
	s_waitcnt vmcnt(14)
	v_cvt_pk_bf16_f32 v58, v60, v61
	v_cvt_pk_bf16_f32 v59, v62, v63
	ds_write2_b64 v203, v[56:57], v[58:59] offset1:68
	s_waitcnt vmcnt(13)
	v_cvt_pk_bf16_f32 v56, v68, v69
	v_cvt_pk_bf16_f32 v57, v70, v71
	s_waitcnt vmcnt(12)
	v_cvt_pk_bf16_f32 v58, v72, v73
	v_cvt_pk_bf16_f32 v59, v74, v75
	ds_write2_b64 v203, v[56:57], v[58:59] offset0:136 offset1:204
	s_waitcnt vmcnt(11)
	v_cvt_pk_bf16_f32 v56, v76, v77
	v_cvt_pk_bf16_f32 v57, v78, v79
	s_waitcnt vmcnt(10)
	v_cvt_pk_bf16_f32 v58, v84, v85
	v_cvt_pk_bf16_f32 v59, v86, v87
	ds_write2_b64 v146, v[56:57], v[58:59] offset0:16 offset1:84
	s_waitcnt vmcnt(9)
	v_cvt_pk_bf16_f32 v56, v148, v149
	v_cvt_pk_bf16_f32 v57, v150, v151
	s_waitcnt vmcnt(8)
	v_cvt_pk_bf16_f32 v58, v152, v153
	v_cvt_pk_bf16_f32 v59, v154, v155
	ds_write2_b64 v146, v[56:57], v[58:59] offset0:152 offset1:220
	s_waitcnt lgkmcnt(0)
	ds_read_b128 v[56:59], v204
	ds_read_b128 v[60:63], v204 offset:64
	s_waitcnt lgkmcnt(1)
	v_mfma_f32_16x16x32_bf16 v[56:59], v[4:7], v[56:59], 0
	v_sub_u32_e32 v68, v200, v48
	v_cvt_f32_i32_e32 v72, v68
	ds_read_b128 v[68:71], v204 offset:128
	s_waitcnt lgkmcnt(1)
	v_mfma_f32_16x16x32_bf16 v[56:59], v[0:3], v[60:63], v[56:59]
	v_fma_f32 v149, -v177, v114, v52
	v_sub_u32_e32 v52, v199, v48
	v_sub_u32_e32 v48, v201, v48
	v_cvt_f32_i32_e32 v48, v48
	ds_read_b128 v[60:63], v204 offset:192
	v_cvt_f32_i32_e32 v52, v52
	s_waitcnt lgkmcnt(1)
	v_mfma_f32_16x16x32_bf16 v[56:59], v[12:15], v[68:71], v[56:59]
	v_fma_f32 v148, -v177, v48, v55
	v_or_b32_e32 v48, s48, v187
	v_fma_f32 v152, -v177, v52, v53
	v_fma_f32 v150, -v177, v72, v54
	s_waitcnt lgkmcnt(0)
	v_mfma_f32_16x16x32_bf16 v[52:55], v[8:11], v[60:63], v[56:59]
	s_mov_b32 s42, 0x60000
	s_waitcnt lgkmcnt(0)
	s_waitcnt vmcnt(7)
	v_cvt_pk_bf16_f32 v64, v64, v65
	v_sub_u32_e32 v56, v198, v48
	v_cvt_f32_i32_e32 v151, v56
	v_add_co_u32_e32 v56, vcc, s42, v112
	s_mov_b32 s42, 0x62000
	s_nop 0
	v_addc_co_u32_e32 v57, vcc, 0, v113, vcc
	v_add_co_u32_e32 v60, vcc, s42, v112
	v_cvt_pk_bf16_f32 v65, v66, v67
	s_nop 0
	v_addc_co_u32_e32 v61, vcc, 0, v113, vcc
	v_add_co_u32_e32 v68, vcc, s69, v112
	global_load_dwordx4 v[56:59], v[56:57], off nt
	s_nop 0
	global_load_dwordx4 v[60:63], v[60:61], off nt
	v_addc_co_u32_e32 v69, vcc, 0, v113, vcc
	v_add_co_u32_e32 v72, vcc, s70, v112
	s_waitcnt vmcnt(8)
	v_cvt_pk_bf16_f32 v66, v80, v81
	v_addc_co_u32_e32 v73, vcc, 0, v113, vcc
	v_add_co_u32_e32 v76, vcc, s71, v112
	global_load_dwordx4 v[68:71], v[68:69], off nt
	s_nop 0
	global_load_dwordx4 v[72:75], v[72:73], off nt
	v_addc_co_u32_e32 v77, vcc, 0, v113, vcc
	v_add_co_u32_e32 v84, vcc, s72, v112
	v_cvt_pk_bf16_f32 v67, v82, v83
	s_nop 0
	v_addc_co_u32_e32 v85, vcc, 0, v113, vcc
	v_add_co_u32_e32 v114, vcc, s74, v112
	global_load_dwordx4 v[76:79], v[76:77], off nt
	s_nop 0
	global_load_dwordx4 v[84:87], v[84:85], off nt
	v_addc_co_u32_e32 v115, vcc, 0, v113, vcc
	v_add_co_u32_e32 v158, vcc, s76, v112
	v_fma_f32 v174, -v177, v151, v52
	s_nop 0
	v_addc_co_u32_e32 v159, vcc, 0, v113, vcc
	global_load_dwordx4 v[154:157], v[114:115], off nt
	s_nop 0
	global_load_dwordx4 v[158:161], v[158:159], off nt
	ds_write2_b64 v203, v[64:65], v[66:67] offset1:68
	s_waitcnt vmcnt(13)
	v_cvt_pk_bf16_f32 v64, v88, v89
	v_cvt_pk_bf16_f32 v65, v90, v91
	s_waitcnt vmcnt(12)
	v_cvt_pk_bf16_f32 v66, v92, v93
	v_cvt_pk_bf16_f32 v67, v94, v95
	ds_write2_b64 v203, v[64:65], v[66:67] offset0:136 offset1:204
	s_waitcnt vmcnt(11)
	v_cvt_pk_bf16_f32 v64, v96, v97
	v_add_co_u32_e32 v96, vcc, s77, v112
	s_waitcnt vmcnt(10)
	v_cvt_pk_bf16_f32 v66, v100, v101
	v_addc_co_u32_e32 v97, vcc, 0, v113, vcc
	v_add_co_u32_e32 v100, vcc, s78, v112
	v_cvt_pk_bf16_f32 v65, v98, v99
	v_cvt_pk_bf16_f32 v67, v102, v103
	v_addc_co_u32_e32 v101, vcc, 0, v113, vcc
	ds_write2_b64 v146, v[64:65], v[66:67] offset0:16 offset1:84
	s_waitcnt vmcnt(9)
	v_cvt_pk_bf16_f32 v64, v104, v105
	v_add_co_u32_e32 v104, vcc, s79, v112
	v_cvt_pk_bf16_f32 v65, v106, v107
	s_nop 0
	v_addc_co_u32_e32 v105, vcc, 0, v113, vcc
	s_waitcnt vmcnt(8)
	v_cvt_pk_bf16_f32 v66, v108, v109
	v_cvt_pk_bf16_f32 v67, v110, v111
	v_add_co_u32_e32 v108, vcc, s80, v112
	ds_write2_b64 v146, v[64:65], v[66:67] offset0:152 offset1:220
	s_nop 0
	v_addc_co_u32_e32 v109, vcc, 0, v113, vcc
	s_waitcnt lgkmcnt(0)
	v_add_co_u32_e32 v114, vcc, s81, v112
	ds_read_b128 v[64:67], v204
	ds_read_b128 v[80:83], v204 offset:64
	ds_read_b128 v[88:91], v204 offset:128
	ds_read_b128 v[92:95], v204 offset:192
	v_addc_co_u32_e32 v115, vcc, 0, v113, vcc
	s_waitcnt lgkmcnt(0)
	v_add_co_u32_e32 v166, vcc, s82, v112
	global_load_dwordx4 v[96:99], v[96:97], off nt
	s_nop 0
	global_load_dwordx4 v[100:103], v[100:101], off nt
	v_addc_co_u32_e32 v167, vcc, 0, v113, vcc
	global_load_dwordx4 v[104:107], v[104:105], off nt
	s_nop 0
	global_load_dwordx4 v[108:111], v[108:109], off nt
	s_nop 0
	global_load_dwordx4 v[162:165], v[114:115], off nt
	s_nop 0
	global_load_dwordx4 v[166:169], v[166:167], off nt
	v_add_co_u32_e32 v114, vcc, s83, v112
	s_waitcnt lgkmcnt(3)
	v_mfma_f32_16x16x32_bf16 v[64:67], v[4:7], v[64:67], 0
	v_addc_co_u32_e32 v115, vcc, 0, v113, vcc
	v_add_co_u32_e32 v112, vcc, s84, v112
	global_load_dwordx4 v[170:173], v[114:115], off nt
	s_nop 0
	v_addc_co_u32_e32 v113, vcc, 0, v113, vcc
	global_load_dwordx4 v[112:115], v[112:113], off nt
	s_waitcnt vmcnt(15)
	v_cvt_pk_bf16_f32 v56, v56, v57
	v_cvt_pk_bf16_f32 v57, v58, v59
	s_waitcnt vmcnt(14)
	v_cvt_pk_bf16_f32 v58, v60, v61
	v_cvt_pk_bf16_f32 v59, v62, v63
	s_waitcnt lgkmcnt(2)
	v_mfma_f32_16x16x32_bf16 v[64:67], v[0:3], v[80:83], v[64:67]
	ds_write2_b64 v203, v[56:57], v[58:59] offset1:68
	s_waitcnt vmcnt(13)
	v_cvt_pk_bf16_f32 v56, v68, v69
	v_cvt_pk_bf16_f32 v57, v70, v71
	s_waitcnt vmcnt(12)
	v_cvt_pk_bf16_f32 v58, v72, v73
	v_cvt_pk_bf16_f32 v59, v74, v75
	ds_write2_b64 v203, v[56:57], v[58:59] offset0:136 offset1:204
	s_waitcnt vmcnt(11)
	v_cvt_pk_bf16_f32 v56, v76, v77
	v_cvt_pk_bf16_f32 v57, v78, v79
	s_waitcnt vmcnt(10)
	v_cvt_pk_bf16_f32 v58, v84, v85
	v_cvt_pk_bf16_f32 v59, v86, v87
	v_sub_u32_e32 v52, v199, v48
	v_sub_u32_e32 v151, v200, v48
	v_sub_u32_e32 v48, v201, v48
	ds_write2_b64 v146, v[56:57], v[58:59] offset0:16 offset1:84
	s_waitcnt vmcnt(9)
	v_cvt_pk_bf16_f32 v56, v154, v155
	v_cvt_pk_bf16_f32 v57, v156, v157
	s_waitcnt vmcnt(8)
	v_cvt_pk_bf16_f32 v58, v158, v159
	v_cvt_pk_bf16_f32 v59, v160, v161
	v_cvt_f32_i32_e32 v48, v48
	ds_write2_b64 v146, v[56:57], v[58:59] offset0:152 offset1:220
	v_cvt_f32_i32_e32 v52, v52
	v_cvt_f32_i32_e32 v80, v151
	s_waitcnt lgkmcnt(5)
	v_mfma_f32_16x16x32_bf16 v[64:67], v[12:15], v[88:91], v[64:67]
	s_waitcnt lgkmcnt(0)
	ds_read_b128 v[56:59], v204
	ds_read_b128 v[60:63], v204 offset:64
	v_fma_f32 v240, -v177, v48, v55
	v_or_b32_e32 v48, s48, v188
	v_fma_f32 v175, -v177, v52, v53
	v_fma_f32 v237, -v177, v80, v54
	s_waitcnt lgkmcnt(6)
	v_mfma_f32_16x16x32_bf16 v[52:55], v[8:11], v[92:95], v[64:67]
	s_nop 2
	v_sub_u32_e32 v64, v198, v48
	v_cvt_f32_i32_e32 v64, v64
	s_waitcnt lgkmcnt(1)
	v_mfma_f32_16x16x32_bf16 v[56:59], v[4:7], v[56:59], 0
	s_nop 0
	v_fma_f32 v154, -v177, v64, v52
	v_sub_u32_e32 v64, v200, v48
	v_cvt_f32_i32_e32 v68, v64
	ds_read_b128 v[64:67], v204 offset:128
	s_waitcnt lgkmcnt(1)
	v_mfma_f32_16x16x32_bf16 v[56:59], v[0:3], v[60:63], v[56:59]
	v_sub_u32_e32 v52, v199, v48
	v_sub_u32_e32 v48, v201, v48
	v_cvt_f32_i32_e32 v48, v48
	ds_read_b128 v[60:63], v204 offset:192
	v_cvt_f32_i32_e32 v52, v52
	s_waitcnt lgkmcnt(1)
	v_mfma_f32_16x16x32_bf16 v[56:59], v[12:15], v[64:67], v[56:59]
	v_fma_f32 v242, -v177, v48, v55
	v_or_b32_e32 v48, s48, v189
	v_fma_f32 v156, -v177, v52, v53
	v_fma_f32 v158, -v177, v68, v54
	s_waitcnt lgkmcnt(0)
	v_mfma_f32_16x16x32_bf16 v[52:55], v[8:11], v[60:63], v[56:59]
	s_waitcnt lgkmcnt(0)
	v_sub_u32_e32 v64, v199, v48
	v_cvt_f32_i32_e32 v68, v64
	s_nop 0
	v_sub_u32_e32 v56, v201, v48
	v_cvt_f32_i32_e32 v60, v56
	s_waitcnt vmcnt(7)
	v_cvt_pk_bf16_f32 v56, v96, v97
	v_cvt_pk_bf16_f32 v57, v98, v99
	s_waitcnt vmcnt(6)
	v_cvt_pk_bf16_f32 v58, v100, v101
	v_cvt_pk_bf16_f32 v59, v102, v103
	ds_write2_b64 v203, v[56:57], v[58:59] offset1:68
	s_waitcnt vmcnt(5)
	v_cvt_pk_bf16_f32 v56, v104, v105
	v_cvt_pk_bf16_f32 v57, v106, v107
	s_waitcnt vmcnt(4)
	v_cvt_pk_bf16_f32 v58, v108, v109
	v_cvt_pk_bf16_f32 v59, v110, v111
	ds_write2_b64 v203, v[56:57], v[58:59] offset0:136 offset1:204
	s_waitcnt vmcnt(3)
	v_cvt_pk_bf16_f32 v56, v162, v163
	v_cvt_pk_bf16_f32 v57, v164, v165
	s_waitcnt vmcnt(2)
	v_cvt_pk_bf16_f32 v58, v166, v167
	v_cvt_pk_bf16_f32 v59, v168, v169
	ds_write2_b64 v146, v[56:57], v[58:59] offset0:16 offset1:84
	s_waitcnt vmcnt(1)
	v_cvt_pk_bf16_f32 v56, v170, v171
	v_cvt_pk_bf16_f32 v57, v172, v173
	s_waitcnt vmcnt(0)
	v_cvt_pk_bf16_f32 v58, v112, v113
	v_cvt_pk_bf16_f32 v59, v114, v115
	ds_write2_b64 v146, v[56:57], v[58:59] offset0:152 offset1:220
	s_waitcnt lgkmcnt(0)
	ds_read_b128 v[56:59], v204
	v_fma_f32 v243, -v177, v60, v55
	ds_read_b128 v[60:63], v204 offset:64
	s_waitcnt lgkmcnt(1)
	v_mfma_f32_16x16x32_bf16 v[56:59], v[4:7], v[56:59], 0
	ds_read_b128 v[64:67], v204 offset:128
	v_sub_u32_e32 v55, v200, v48
	v_sub_u32_e32 v48, v198, v48
	s_waitcnt lgkmcnt(1)
	v_mfma_f32_16x16x32_bf16 v[56:59], v[0:3], v[60:63], v[56:59]
	v_cvt_f32_i32_e32 v48, v48
	ds_read_b128 v[60:63], v204 offset:192
	v_cvt_f32_i32_e32 v55, v55
	s_waitcnt lgkmcnt(1)
	v_mfma_f32_16x16x32_bf16 v[56:59], v[12:15], v[64:67], v[56:59]
	v_fma_f32 v157, -v177, v48, v52
	v_or_b32_e32 v48, s48, v190
	v_fma_f32 v146, -v177, v55, v54
	v_fma_f32 v160, -v177, v68, v53
	s_waitcnt lgkmcnt(0)
	v_mfma_f32_16x16x32_bf16 v[52:55], v[8:11], v[60:63], v[56:59]
	v_lshl_add_u64 v[108:109], s[54:55], 0, v[136:137]
	s_waitcnt lgkmcnt(0)
	s_nop 1
	v_sub_u32_e32 v56, v198, v48
	v_sub_u32_e32 v57, v199, v48
	v_sub_u32_e32 v58, v200, v48
	v_sub_u32_e32 v48, v201, v48
	v_cvt_f32_i32_e32 v48, v48
	v_cvt_f32_i32_e32 v56, v56
	v_cvt_f32_i32_e32 v57, v57
	v_cvt_f32_i32_e32 v58, v58
	v_fma_f32 v245, -v177, v48, v55
	v_max_f32_e32 v48, v135, v49
	v_max3_f32 v48, v48, v147, v149
	v_fma_f32 v241, -v177, v56, v52
	v_max3_f32 v48, v48, v174, v154
	v_max3_f32 v48, v48, v157, v241
	ds_swizzle_b32 v102, v48 offset:swizzle(SWAP,1)
	v_fma_f32 v161, -v177, v57, v53
	v_add_co_u32_e32 v56, vcc, s44, v108
	v_fma_f32 v244, -v177, v58, v54
	s_waitcnt lgkmcnt(0)
	v_max_f32_e32 v102, v102, v102
	v_max_f32_e32 v48, v48, v102
	ds_swizzle_b32 v110, v48 offset:swizzle(SWAP,2)
	v_addc_co_u32_e32 v57, vcc, 0, v109, vcc
	v_add_co_u32_e32 v60, vcc, s49, v108
	s_waitcnt lgkmcnt(0)
	v_max_f32_e32 v110, v110, v110
	v_max_f32_e32 v48, v48, v110
	ds_swizzle_b32 v112, v48 offset:swizzle(SWAP,4)
	v_addc_co_u32_e32 v61, vcc, 0, v109, vcc
	v_add_co_u32_e32 v64, vcc, s56, v108
	s_waitcnt lgkmcnt(0)
	v_max_f32_e32 v112, v112, v112
	v_max_f32_e32 v48, v48, v112
	ds_swizzle_b32 v151, v48 offset:swizzle(SWAP,8)
	v_addc_co_u32_e32 v65, vcc, 0, v109, vcc
	v_add_co_u32_e32 v68, vcc, s57, v108
	s_waitcnt lgkmcnt(0)
	v_max3_f32 v48, v145, v48, v151
	v_max_f32_e32 v151, v133, v50
	v_max3_f32 v151, v151, v141, v152
	v_max3_f32 v151, v151, v175, v156
	v_max3_f32 v151, v151, v160, v161
	ds_swizzle_b32 v153, v151 offset:swizzle(SWAP,1)
	v_sub_f32_e32 v135, v135, v48
	v_exp_f32_e32 v159, v135
	v_sub_f32_e32 v49, v49, v48
	v_exp_f32_e32 v155, v49
	s_waitcnt lgkmcnt(0)
	v_max_f32_e32 v135, v153, v153
	v_max_f32_e32 v135, v151, v135
	v_sub_f32_e32 v49, v147, v48
	ds_swizzle_b32 v147, v135 offset:swizzle(SWAP,2)
	v_exp_f32_e32 v153, v49
	v_sub_f32_e32 v49, v149, v48
	v_exp_f32_e32 v151, v49
	v_sub_f32_e32 v49, v174, v48
	s_waitcnt lgkmcnt(0)
	v_max_f32_e32 v147, v147, v147
	v_max_f32_e32 v135, v135, v147
	ds_swizzle_b32 v162, v135 offset:swizzle(SWAP,4)
	v_exp_f32_e32 v149, v49
	v_sub_f32_e32 v49, v154, v48
	v_exp_f32_e32 v147, v49
	v_sub_f32_e32 v49, v157, v48
	s_waitcnt lgkmcnt(0)
	v_max_f32_e32 v154, v162, v162
	v_max_f32_e32 v157, v130, v51
	v_addc_co_u32_e32 v69, vcc, 0, v109, vcc
	v_max_f32_e32 v135, v135, v154
	v_max3_f32 v157, v157, v140, v150
	v_add_co_u32_e32 v72, vcc, s58, v108
	ds_swizzle_b32 v154, v135 offset:swizzle(SWAP,8)
	v_max3_f32 v157, v157, v237, v158
	v_addc_co_u32_e32 v73, vcc, 0, v109, vcc
	v_max3_f32 v162, v157, v146, v244
	v_add_co_u32_e32 v76, vcc, s59, v108
	ds_swizzle_b32 v163, v162 offset:swizzle(SWAP,1)
	s_nop 0
	v_addc_co_u32_e32 v77, vcc, 0, v109, vcc
	v_add_co_u32_e32 v80, vcc, s60, v108
	v_exp_f32_e32 v157, v49
	s_nop 0
	v_addc_co_u32_e32 v81, vcc, 0, v109, vcc
	s_waitcnt lgkmcnt(1)
	v_max3_f32 v49, v144, v135, v154
	v_add_co_u32_e32 v84, vcc, s61, v108
	v_sub_f32_e32 v133, v133, v49
	s_nop 0
	v_addc_co_u32_e32 v85, vcc, 0, v109, vcc
	v_exp_f32_e32 v174, v133
	s_waitcnt lgkmcnt(0)
	v_max_f32_e32 v133, v163, v163
	v_add_co_u32_e32 v88, vcc, s62, v108
	v_max_f32_e32 v133, v162, v133
	s_nop 0
	v_addc_co_u32_e32 v89, vcc, 0, v109, vcc
	ds_swizzle_b32 v135, v133 offset:swizzle(SWAP,2)
	v_add_co_u32_e32 v92, vcc, s63, v108
	v_sub_f32_e32 v50, v50, v49
	s_nop 0
	v_addc_co_u32_e32 v93, vcc, 0, v109, vcc
	v_add_co_u32_e32 v96, vcc, s64, v108
	v_exp_f32_e32 v172, v50
	s_nop 0
	v_addc_co_u32_e32 v97, vcc, 0, v109, vcc
	v_sub_f32_e32 v50, v141, v49
	v_add_co_u32_e32 v100, vcc, s65, v108
	v_exp_f32_e32 v170, v50
	s_waitcnt lgkmcnt(0)
	v_max_f32_e32 v50, v135, v135
	v_addc_co_u32_e32 v101, vcc, 0, v109, vcc
	v_max_f32_e32 v50, v133, v50
	v_add_co_u32_e32 v104, vcc, s66, v108
	ds_swizzle_b32 v133, v50 offset:swizzle(SWAP,4)
	s_nop 0
	v_addc_co_u32_e32 v105, vcc, 0, v109, vcc
	v_add_co_u32_e32 v110, vcc, s67, v108
	s_waitcnt lgkmcnt(0)
	v_max_f32_e32 v133, v133, v133
	v_addc_co_u32_e32 v111, vcc, 0, v109, vcc
	v_add_co_u32_e32 v112, vcc, s68, v108
	global_load_dwordx4 v[52:55], v[108:109], off nt
	s_nop 0
	global_load_dwordx4 v[56:59], v[56:57], off nt
	v_addc_co_u32_e32 v113, vcc, 0, v109, vcc
	global_load_dwordx4 v[60:63], v[60:61], off nt
	s_nop 0
	global_load_dwordx4 v[64:67], v[64:65], off nt
	s_nop 0
	global_load_dwordx4 v[68:71], v[68:69], off nt
	s_nop 0
	global_load_dwordx4 v[72:75], v[72:73], off nt
	s_nop 0
	global_load_dwordx4 v[76:79], v[76:77], off nt
	s_nop 0
	global_load_dwordx4 v[80:83], v[80:81], off nt
	s_nop 0
	global_load_dwordx4 v[84:87], v[84:85], off nt
	s_nop 0
	global_load_dwordx4 v[88:91], v[88:89], off nt
	s_nop 0
	global_load_dwordx4 v[92:95], v[92:93], off nt
	s_nop 0
	global_load_dwordx4 v[96:99], v[96:97], off nt
	s_nop 0
	global_load_dwordx4 v[100:103], v[100:101], off nt
	s_nop 0
	global_load_dwordx4 v[104:107], v[104:105], off nt
	s_nop 0
	global_load_dwordx4 v[108:111], v[110:111], off nt
	s_nop 0
	global_load_dwordx4 v[112:115], v[112:113], off nt
	v_max_f32_e32 v50, v50, v133
	ds_swizzle_b32 v133, v50 offset:swizzle(SWAP,8)
	v_sub_f32_e32 v135, v152, v49
	v_exp_f32_e32 v168, v135
	v_sub_f32_e32 v135, v175, v49
	v_exp_f32_e32 v166, v135
	s_waitcnt lgkmcnt(0)
	v_max3_f32 v50, v143, v50, v133
	v_sub_f32_e32 v51, v51, v50
	v_sub_f32_e32 v135, v156, v49
	v_exp_f32_e32 v173, v51
	v_sub_f32_e32 v51, v161, v49
	v_exp_f32_e32 v164, v135
	v_sub_f32_e32 v135, v160, v49
	v_exp_f32_e32 v160, v51
	v_sub_f32_e32 v51, v140, v50
	v_exp_f32_e32 v171, v51
	v_sub_f32_e32 v51, v150, v50
	v_exp_f32_e32 v169, v51
	v_sub_f32_e32 v51, v237, v50
	v_exp_f32_e32 v167, v51
	v_sub_f32_e32 v51, v158, v50
	v_exp_f32_e32 v165, v51
	v_max_f32_e32 v51, v131, v132
	v_max3_f32 v51, v51, v134, v148
	v_max3_f32 v51, v51, v240, v242
	v_sub_f32_e32 v130, v130, v50
	v_max3_f32 v51, v51, v243, v245
	v_exp_f32_e32 v175, v130
	ds_swizzle_b32 v130, v51 offset:swizzle(SWAP,1)
	v_sub_f32_e32 v133, v146, v50
	v_exp_f32_e32 v163, v133
	v_pk_add_f32 v[238:239], v[174:175], 0 op_sel_hi:[1,0]
	v_sub_f32_e32 v133, v244, v50
	s_waitcnt lgkmcnt(0)
	v_max_f32_e32 v130, v130, v130
	v_max_f32_e32 v51, v51, v130
	ds_swizzle_b32 v130, v51 offset:swizzle(SWAP,2)
	v_pk_add_f32 v[238:239], v[172:173], v[238:239]
	v_exp_f32_e32 v162, v135
	v_exp_f32_e32 v161, v133
	v_pk_add_f32 v[140:141], v[170:171], v[238:239]
	s_waitcnt lgkmcnt(0)
	v_max_f32_e32 v130, v130, v130
	v_max_f32_e32 v51, v51, v130
	ds_swizzle_b32 v130, v51 offset:swizzle(SWAP,4)
	v_pk_add_f32 v[140:141], v[168:169], v[140:141]
	v_sub_f32_e32 v145, v145, v48
	v_pk_add_f32 v[140:141], v[166:167], v[140:141]
	s_waitcnt lgkmcnt(0)
	v_max_f32_e32 v130, v130, v130
	v_max_f32_e32 v51, v51, v130
	ds_swizzle_b32 v133, v51 offset:swizzle(SWAP,8)
	v_pk_add_f32 v[140:141], v[164:165], v[140:141]
	v_sub_f32_e32 v130, v241, v48
	v_pk_add_f32 v[140:141], v[162:163], v[140:141]
	v_exp_f32_e32 v241, v130
	v_pk_add_f32 v[140:141], v[160:161], v[140:141]
	s_waitcnt lgkmcnt(0)
	v_max3_f32 v51, v142, v51, v133
	ds_swizzle_b32 v238, v140 offset:swizzle(SWAP,1)
	ds_swizzle_b32 v239, v141 offset:swizzle(SWAP,1)
	v_sub_f32_e32 v131, v131, v51
	v_exp_f32_e32 v158, v131
	v_sub_f32_e32 v131, v132, v51
	v_exp_f32_e32 v154, v131
	v_sub_f32_e32 v131, v134, v51
	v_exp_f32_e32 v152, v131
	v_sub_f32_e32 v131, v148, v51
	v_exp_f32_e32 v150, v131
	v_sub_f32_e32 v131, v240, v51
	s_waitcnt lgkmcnt(0)
	v_pk_add_f32 v[140:141], v[140:141], v[238:239]
	v_pk_add_f32 v[238:239], v[158:159], 0 op_sel_hi:[1,0]
	v_exp_f32_e32 v148, v131
	v_sub_f32_e32 v131, v242, v51
	v_pk_add_f32 v[238:239], v[154:155], v[238:239]
	v_exp_f32_e32 v146, v131
	v_sub_f32_e32 v131, v243, v51
	v_exp_f32_e32 v156, v131
	v_sub_f32_e32 v131, v245, v51
	v_pk_add_f32 v[134:135], v[152:153], v[238:239]
	v_exp_f32_e32 v240, v131
	v_pk_add_f32 v[134:135], v[150:151], v[134:135]
	v_cvt_pk_bf16_f32 v159, v159, s0
	v_pk_add_f32 v[134:135], v[148:149], v[134:135]
	ds_write_b16 v205, v159 offset:8192
	v_pk_add_f32 v[134:135], v[146:147], v[134:135]
	v_cvt_pk_bf16_f32 v159, v174, s0
	v_pk_add_f32 v[134:135], v[156:157], v[134:135]
	ds_write_b16 v206, v159 offset:8192
	v_pk_add_f32 v[134:135], v[240:241], v[134:135]
	ds_swizzle_b32 v239, v135 offset:swizzle(SWAP,1)
	ds_swizzle_b32 v238, v134 offset:swizzle(SWAP,1)
	v_cvt_pk_bf16_f32 v159, v175, s0
	v_cvt_pk_bf16_f32 v158, v158, s0
	v_cvt_pk_bf16_f32 v155, v155, s0
	v_exp_f32_e32 v130, v145
	v_sub_f32_e32 v131, v144, v49
	s_waitcnt lgkmcnt(0)
	v_pk_add_f32 v[144:145], v[134:135], v[238:239]
	ds_write_b16 v207, v159 offset:8192
	ds_write_b16 v208, v158 offset:8192
	ds_write_b16 v209, v155 offset:8192
	v_cvt_pk_bf16_f32 v155, v172, s0
	ds_swizzle_b32 v132, v140 offset:swizzle(SWAP,2)
	ds_swizzle_b32 v133, v141 offset:swizzle(SWAP,2)
	ds_swizzle_b32 v239, v145 offset:swizzle(SWAP,2)
	ds_swizzle_b32 v238, v144 offset:swizzle(SWAP,2)
	ds_write_b16 v210, v155 offset:8192
	v_cvt_pk_bf16_f32 v155, v173, s0
	v_cvt_pk_bf16_f32 v154, v154, s0
	v_cvt_pk_bf16_f32 v153, v153, s0
	ds_write_b16 v211, v155 offset:8192
	ds_write_b16 v212, v154 offset:8192
	ds_write_b16 v213, v153 offset:8192
	v_cvt_pk_bf16_f32 v153, v170, s0
	ds_write_b16 v214, v153 offset:8192
	v_cvt_pk_bf16_f32 v153, v171, s0
	v_cvt_pk_bf16_f32 v152, v152, s0
	v_cvt_pk_bf16_f32 v151, v151, s0
	ds_write_b16 v215, v153 offset:8192
	ds_write_b16 v216, v152 offset:8192
	ds_write_b16 v217, v151 offset:8192
	v_cvt_pk_bf16_f32 v151, v168, s0
	ds_write_b16 v218, v151 offset:8192
	v_cvt_pk_bf16_f32 v151, v169, s0
	v_cvt_pk_bf16_f32 v150, v150, s0
	v_cvt_pk_bf16_f32 v149, v149, s0
	s_waitcnt lgkmcnt(11)
	v_pk_add_f32 v[132:133], v[140:141], v[132:133]
	s_waitcnt lgkmcnt(9)
	v_pk_add_f32 v[144:145], v[144:145], v[238:239]
	ds_write_b16 v219, v151 offset:8192
	ds_write_b16 v220, v150 offset:8192
	ds_write_b16 v221, v149 offset:8192
	v_cvt_pk_bf16_f32 v149, v166, s0
	ds_swizzle_b32 v140, v132 offset:swizzle(SWAP,4)
	ds_swizzle_b32 v141, v133 offset:swizzle(SWAP,4)
	ds_swizzle_b32 v239, v145 offset:swizzle(SWAP,4)
	ds_swizzle_b32 v238, v144 offset:swizzle(SWAP,4)
	ds_write_b16 v222, v149 offset:8192
	v_cvt_pk_bf16_f32 v149, v167, s0
	v_cvt_pk_bf16_f32 v148, v148, s0
	v_cvt_pk_bf16_f32 v147, v147, s0
	ds_write_b16 v223, v149 offset:8192
	ds_write_b16 v224, v148 offset:8192
	ds_write_b16 v225, v147 offset:8192
	v_cvt_pk_bf16_f32 v147, v164, s0
	v_cvt_pk_bf16_f32 v146, v146, s0
	ds_write_b16 v226, v147 offset:8192
	v_cvt_pk_bf16_f32 v147, v165, s0
	ds_write_b16 v228, v146 offset:8192
	v_cvt_pk_bf16_f32 v146, v157, s0
	ds_write_b16 v227, v147 offset:8192
	ds_write_b16 v229, v146 offset:8192
	v_cvt_pk_bf16_f32 v146, v162, s0
	ds_write_b16 v230, v146 offset:8192
	v_cvt_pk_bf16_f32 v146, v163, s0
	v_sub_f32_e32 v134, v143, v50
	s_waitcnt lgkmcnt(11)
	v_pk_add_f32 v[132:133], v[132:133], v[140:141]
	v_sub_f32_e32 v135, v142, v51
	s_waitcnt lgkmcnt(9)
	v_pk_add_f32 v[142:143], v[144:145], v[238:239]
	ds_write_b16 v231, v146 offset:8192
	v_cvt_pk_bf16_f32 v146, v156, s0
	v_exp_f32_e32 v131, v131
	v_exp_f32_e32 v134, v134
	ds_swizzle_b32 v140, v132 offset:swizzle(SWAP,8)
	ds_swizzle_b32 v141, v133 offset:swizzle(SWAP,8)
	v_exp_f32_e32 v135, v135
	ds_swizzle_b32 v145, v143 offset:swizzle(SWAP,8)
	ds_swizzle_b32 v144, v142 offset:swizzle(SWAP,8)
	ds_write_b16 v232, v146 offset:8192
	v_cvt_pk_bf16_f32 v146, v241, s0
	ds_write_b16 v233, v146 offset:8192
	v_cvt_pk_bf16_f32 v146, v160, s0
	ds_write_b16 v234, v146 offset:8192
	v_cvt_pk_bf16_f32 v146, v161, s0
	ds_write_b16 v235, v146 offset:8192
	v_cvt_pk_bf16_f32 v146, v240, s0
	v_pk_mul_f32 v[46:47], v[46:47], v[134:135]
	v_pk_mul_f32 v[44:45], v[44:45], v[130:131]
	v_pk_mul_f32 v[42:43], v[42:43], v[134:135]
	v_pk_mul_f32 v[40:41], v[40:41], v[130:131]
	v_pk_mul_f32 v[38:39], v[38:39], v[134:135]
	v_pk_mul_f32 v[36:37], v[36:37], v[130:131]
	v_pk_mul_f32 v[34:35], v[34:35], v[134:135]
	v_pk_mul_f32 v[32:33], v[32:33], v[130:131]
	v_pk_mul_f32 v[30:31], v[30:31], v[134:135]
	v_pk_mul_f32 v[28:29], v[28:29], v[130:131]
	v_pk_mul_f32 v[26:27], v[26:27], v[134:135]
	v_pk_mul_f32 v[24:25], v[24:25], v[130:131]
	v_pk_mul_f32 v[22:23], v[22:23], v[134:135]
	v_pk_mul_f32 v[20:21], v[20:21], v[130:131]
	v_pk_mul_f32 v[18:19], v[18:19], v[134:135]
	v_pk_mul_f32 v[16:17], v[16:17], v[130:131]
	ds_write_b16 v236, v146 offset:8192
	v_lshl_add_u64 v[146:147], v[124:125], 0, s[52:53]
	s_mov_b64 s[52:53], 0
	v_mov_b32_e32 v148, v202
	s_branch .LBB0_1612
.LBB0_1612:
	v_lshl_add_u64 v[174:175], v[146:147], 0, s[52:53]
	v_add_co_u32_e32 v166, vcc, 0x20000, v174
	s_nop 1
	v_addc_co_u32_e32 v167, vcc, 0, v175, vcc
	global_load_dwordx4 v[166:169], v[166:167], off nt
	v_add_co_u32_e32 v170, vcc, 0x22000, v174
	s_nop 1
	v_addc_co_u32_e32 v171, vcc, 0, v175, vcc
	global_load_dwordx4 v[170:173], v[170:171], off nt
	v_add_co_u32_e32 v238, vcc, 0x24000, v174
	s_nop 1
	v_addc_co_u32_e32 v239, vcc, 0, v175, vcc
	global_load_dwordx4 v[238:241], v[238:239], off nt
	v_add_co_u32_e32 v242, vcc, 0x26000, v174
	s_nop 1
	v_addc_co_u32_e32 v243, vcc, 0, v175, vcc
	global_load_dwordx4 v[242:245], v[242:243], off nt
	v_add_co_u32_e32 v246, vcc, 0x28000, v174
	s_nop 1
	v_addc_co_u32_e32 v247, vcc, 0, v175, vcc
	global_load_dwordx4 v[246:249], v[246:247], off nt
	v_add_co_u32_e32 v250, vcc, 0x2a000, v174
	s_nop 1
	v_addc_co_u32_e32 v251, vcc, 0, v175, vcc
	global_load_dwordx4 v[250:253], v[250:251], off nt
	v_mov_b32_e32 v149, v121
	v_mov_b32_e32 v154, v117
	s_waitcnt vmcnt(21)
	v_cvt_pk_bf16_f32 v150, v52, v53
	v_add_u32_e32 v157, 2, v154
	v_lshlrev_b32_e32 v153, 2, v154
	v_lshlrev_b32_e32 v159, 2, v157
	v_and_b32_e32 v155, 12, v153
	v_bfe_u32 v153, v154, 2, 2
	v_lshlrev_b32_e32 v158, 8, v157
	v_and_b32_e32 v159, 12, v159
	v_bfe_u32 v157, v157, 2, 2
	v_bitop3_b32 v153, v155, v119, v153 bitop3:0x36
	v_bitop3_b32 v157, v159, v119, v157 bitop3:0x36
	v_lshlrev_b32_e32 v152, 8, v154
	v_lshl_add_u32 v153, v153, 4, s39
	v_lshl_add_u32 v157, v157, 4, s39
	v_add3_u32 v156, v153, v152, v123
	s_waitcnt vmcnt(20)
	v_cvt_pk_bf16_f32 v152, v56, v57
	v_cvt_pk_bf16_f32 v153, v58, v59
	v_add3_u32 v157, v157, v158, v123
	ds_write_b64 v157, v[152:153]
	v_add_u32_e32 v157, 4, v154
	v_lshlrev_b32_e32 v158, 8, v157
	v_bfe_u32 v157, v157, 2, 2
	v_bitop3_b32 v157, v157, v119, v155 bitop3:0x36
	v_lshl_add_u32 v157, v157, 4, s39
	s_waitcnt vmcnt(19)
	v_cvt_pk_bf16_f32 v152, v60, v61
	v_cvt_pk_bf16_f32 v153, v62, v63
	v_add3_u32 v157, v157, v158, v123
	ds_write_b64 v157, v[152:153]
	v_add_u32_e32 v157, 6, v154
	v_lshlrev_b32_e32 v159, 2, v157
	v_lshlrev_b32_e32 v158, 8, v157
	v_and_b32_e32 v159, 12, v159
	v_bfe_u32 v157, v157, 2, 2
	v_bitop3_b32 v157, v159, v119, v157 bitop3:0x36
	v_lshl_add_u32 v157, v157, 4, s39
	s_waitcnt vmcnt(18)
	v_cvt_pk_bf16_f32 v152, v64, v65
	v_cvt_pk_bf16_f32 v153, v66, v67
	v_add3_u32 v157, v157, v158, v123
	ds_write_b64 v157, v[152:153]
	v_add_u32_e32 v157, 8, v154
	v_lshlrev_b32_e32 v158, 8, v157
	v_bfe_u32 v157, v157, 2, 2
	v_bitop3_b32 v157, v157, v119, v155 bitop3:0x36
	v_lshl_add_u32 v157, v157, 4, s39
	s_waitcnt vmcnt(17)
	v_cvt_pk_bf16_f32 v152, v68, v69
	v_cvt_pk_bf16_f32 v153, v70, v71
	v_add3_u32 v157, v157, v158, v123
	ds_write_b64 v157, v[152:153]
	v_add_u32_e32 v157, 10, v154
	v_lshlrev_b32_e32 v159, 2, v157
	v_lshlrev_b32_e32 v158, 8, v157
	v_and_b32_e32 v159, 12, v159
	v_bfe_u32 v157, v157, 2, 2
	v_bitop3_b32 v157, v159, v119, v157 bitop3:0x36
	v_lshl_add_u32 v157, v157, 4, s39
	s_waitcnt vmcnt(16)
	v_cvt_pk_bf16_f32 v152, v72, v73
	v_cvt_pk_bf16_f32 v153, v74, v75
	v_add3_u32 v157, v157, v158, v123
	ds_write_b64 v157, v[152:153]
	v_add_u32_e32 v157, 12, v154
	v_lshlrev_b32_e32 v158, 8, v157
	v_bfe_u32 v157, v157, 2, 2
	v_bitop3_b32 v157, v157, v119, v155 bitop3:0x36
	v_lshl_add_u32 v157, v157, 4, s39
	s_waitcnt vmcnt(15)
	v_cvt_pk_bf16_f32 v152, v76, v77
	v_cvt_pk_bf16_f32 v153, v78, v79
	v_add3_u32 v157, v157, v158, v123
	ds_write_b64 v157, v[152:153]
	v_add_u32_e32 v157, 14, v154
	v_lshlrev_b32_e32 v159, 2, v157
	v_lshlrev_b32_e32 v158, 8, v157
	v_and_b32_e32 v159, 12, v159
	v_bfe_u32 v157, v157, 2, 2
	v_bitop3_b32 v157, v159, v119, v157 bitop3:0x36
	v_lshl_add_u32 v157, v157, 4, s39
	s_waitcnt vmcnt(14)
	v_cvt_pk_bf16_f32 v152, v80, v81
	v_cvt_pk_bf16_f32 v153, v82, v83
	v_add3_u32 v157, v157, v158, v123
	v_cvt_pk_bf16_f32 v151, v54, v55
	ds_write_b64 v157, v[152:153]
	s_waitcnt vmcnt(13)
	v_cvt_pk_bf16_f32 v152, v84, v85
	v_cvt_pk_bf16_f32 v153, v86, v87
	ds_write2st64_b64 v156, v[150:151], v[152:153] offset1:8
	v_add_u32_e32 v152, 18, v154
	v_lshlrev_b32_e32 v156, 2, v152
	v_lshlrev_b32_e32 v153, 8, v152
	v_and_b32_e32 v156, 12, v156
	v_bfe_u32 v152, v152, 2, 2
	v_bitop3_b32 v152, v156, v119, v152 bitop3:0x36
	v_lshl_add_u32 v152, v152, 4, s39
	s_waitcnt vmcnt(12)
	v_cvt_pk_bf16_f32 v150, v88, v89
	v_cvt_pk_bf16_f32 v151, v90, v91
	v_add3_u32 v152, v152, v153, v123
	ds_write_b64 v152, v[150:151]
	v_add_u32_e32 v152, 20, v154
	v_lshlrev_b32_e32 v153, 8, v152
	v_bfe_u32 v152, v152, 2, 2
	v_bitop3_b32 v152, v152, v119, v155 bitop3:0x36
	v_lshl_add_u32 v152, v152, 4, s39
	s_waitcnt vmcnt(11)
	v_cvt_pk_bf16_f32 v150, v92, v93
	v_cvt_pk_bf16_f32 v151, v94, v95
	v_add3_u32 v152, v152, v153, v123
	ds_write_b64 v152, v[150:151]
	v_add_u32_e32 v152, 22, v154
	v_lshlrev_b32_e32 v156, 2, v152
	v_lshlrev_b32_e32 v153, 8, v152
	v_and_b32_e32 v156, 12, v156
	v_bfe_u32 v152, v152, 2, 2
	v_bitop3_b32 v152, v156, v119, v152 bitop3:0x36
	v_lshl_add_u32 v152, v152, 4, s39
	s_waitcnt vmcnt(10)
	v_cvt_pk_bf16_f32 v150, v96, v97
	v_cvt_pk_bf16_f32 v151, v98, v99
	v_add3_u32 v152, v152, v153, v123
	ds_write_b64 v152, v[150:151]
	v_add_u32_e32 v152, 24, v154
	v_lshlrev_b32_e32 v153, 8, v152
	v_bfe_u32 v152, v152, 2, 2
	v_bitop3_b32 v152, v152, v119, v155 bitop3:0x36
	v_lshl_add_u32 v152, v152, 4, s39
	s_waitcnt vmcnt(9)
	v_cvt_pk_bf16_f32 v150, v100, v101
	v_cvt_pk_bf16_f32 v151, v102, v103
	v_add3_u32 v152, v152, v153, v123
	ds_write_b64 v152, v[150:151]
	v_add_u32_e32 v152, 26, v154
	v_lshlrev_b32_e32 v156, 2, v152
	v_lshlrev_b32_e32 v153, 8, v152
	v_and_b32_e32 v156, 12, v156
	v_bfe_u32 v152, v152, 2, 2
	v_bitop3_b32 v152, v156, v119, v152 bitop3:0x36
	v_lshl_add_u32 v152, v152, 4, s39
	s_waitcnt vmcnt(8)
	v_cvt_pk_bf16_f32 v150, v104, v105
	v_cvt_pk_bf16_f32 v151, v106, v107
	v_add3_u32 v152, v152, v153, v123
	ds_write_b64 v152, v[150:151]
	v_add_u32_e32 v152, 28, v154
	v_lshlrev_b32_e32 v153, 8, v152
	v_bfe_u32 v152, v152, 2, 2
	v_bitop3_b32 v152, v152, v119, v155 bitop3:0x36
	v_lshl_add_u32 v152, v152, 4, s39
	s_waitcnt vmcnt(7)
	v_cvt_pk_bf16_f32 v150, v108, v109
	v_cvt_pk_bf16_f32 v151, v110, v111
	v_add3_u32 v152, v152, v153, v123
	ds_write_b64 v152, v[150:151]
	v_add_u32_e32 v152, 30, v154
	v_lshlrev_b32_e32 v154, 2, v152
	v_lshlrev_b32_e32 v153, 8, v152
	v_and_b32_e32 v154, 12, v154
	v_bfe_u32 v152, v152, 2, 2
	v_bitop3_b32 v152, v154, v119, v152 bitop3:0x36
	v_lshl_add_u32 v152, v152, 4, s39
	s_waitcnt vmcnt(6)
	v_cvt_pk_bf16_f32 v150, v112, v113
	v_cvt_pk_bf16_f32 v151, v114, v115
	v_add3_u32 v152, v152, v153, v123
	ds_write_b64 v152, v[150:151]
	v_lshl_add_u64 v[108:109], v[146:147], 0, s[52:53]
	v_add_co_u32_e32 v76, vcc, 0x2c000, v108
	s_nop 1
	v_addc_co_u32_e32 v77, vcc, 0, v109, vcc
	global_load_dwordx4 v[76:79], v[76:77], off nt
	v_add_co_u32_e32 v80, vcc, 0x2e000, v108
	s_nop 1
	v_addc_co_u32_e32 v81, vcc, 0, v109, vcc
	global_load_dwordx4 v[80:83], v[80:81], off nt
	v_add_co_u32_e32 v84, vcc, 0x30000, v108
	s_nop 1
	v_addc_co_u32_e32 v85, vcc, 0, v109, vcc
	global_load_dwordx4 v[84:87], v[84:85], off nt
	v_add_co_u32_e32 v88, vcc, 0x32000, v108
	s_nop 1
	v_addc_co_u32_e32 v89, vcc, 0, v109, vcc
	global_load_dwordx4 v[88:91], v[88:89], off nt
	v_add_co_u32_e32 v92, vcc, 0x34000, v108
	s_nop 1
	v_addc_co_u32_e32 v93, vcc, 0, v109, vcc
	global_load_dwordx4 v[92:95], v[92:93], off nt
	v_add_co_u32_e32 v96, vcc, 0x36000, v108
	s_nop 1
	v_addc_co_u32_e32 v97, vcc, 0, v109, vcc
	global_load_dwordx4 v[96:99], v[96:97], off nt
	v_add_co_u32_e32 v100, vcc, 0x38000, v108
	s_nop 1
	v_addc_co_u32_e32 v101, vcc, 0, v109, vcc
	global_load_dwordx4 v[100:103], v[100:101], off nt
	v_add_co_u32_e32 v104, vcc, 0x3a000, v108
	s_nop 1
	v_addc_co_u32_e32 v105, vcc, 0, v109, vcc
	global_load_dwordx4 v[104:107], v[104:105], off nt
	v_add_co_u32_e32 v110, vcc, 0x3c000, v108
	s_nop 1
	v_addc_co_u32_e32 v111, vcc, 0, v109, vcc
	v_add_co_u32_e32 v112, vcc, 0x3e000, v108
	s_nop 1
	v_addc_co_u32_e32 v113, vcc, 0, v109, vcc
	global_load_dwordx4 v[108:111], v[110:111], off nt
	s_nop 0
	global_load_dwordx4 v[112:115], v[112:113], off nt
	s_waitcnt lgkmcnt(0)
	ds_read_b128 v[150:153], v148
	v_add_u32_e32 v154, v149, v120
	v_lshlrev_b32_e32 v155, 2, v149
	v_add_u32_e32 v149, v149, v183
	v_and_b32_e32 v162, 12, v155
	v_bfe_u32 v163, v154, 2, 2
	v_bfe_u32 v165, v149, 2, 2
	v_lshl_add_u32 v164, v154, 8, v182
	v_lshl_add_u32 v149, v149, 8, v182
	v_bitop3_b32 v154, v163, v181, v162 bitop3:0x36
	v_bitop3_b32 v155, v165, v181, v162 bitop3:0x36
	v_bitop3_b32 v158, v163, v191, v162 bitop3:0x36
	v_bitop3_b32 v159, v165, v191, v162 bitop3:0x36
	v_lshl_add_u32 v154, v154, 4, v164
	v_lshl_add_u32 v156, v155, 4, v149
	v_lshl_add_u32 v158, v158, 4, v164
	v_lshl_add_u32 v160, v159, 4, v149
	ds_read_b64_tr_b16 v[154:155], v154
	ds_read_b64_tr_b16 v[156:157], v156
	ds_read_b64_tr_b16 v[158:159], v158
	ds_read_b64_tr_b16 v[160:161], v160
	s_waitcnt lgkmcnt(2)
	v_mfma_f32_16x16x32_bf16 v[44:47], v[150:153], v[154:157], v[44:47]
	v_bitop3_b32 v154, v163, v192, v162 bitop3:0x36
	v_bitop3_b32 v155, v165, v192, v162 bitop3:0x36
	v_lshl_add_u32 v154, v154, 4, v164
	s_waitcnt lgkmcnt(0)
	v_mfma_f32_16x16x32_bf16 v[40:43], v[150:153], v[158:161], v[40:43]
	v_bitop3_b32 v158, v163, v193, v162 bitop3:0x36
	v_bitop3_b32 v159, v165, v193, v162 bitop3:0x36
	v_lshl_add_u32 v156, v155, 4, v149
	v_lshl_add_u32 v158, v158, 4, v164
	v_lshl_add_u32 v160, v159, 4, v149
	ds_read_b64_tr_b16 v[154:155], v154
	ds_read_b64_tr_b16 v[156:157], v156
	ds_read_b64_tr_b16 v[158:159], v158
	ds_read_b64_tr_b16 v[160:161], v160
	s_waitcnt lgkmcnt(2)
	v_mfma_f32_16x16x32_bf16 v[36:39], v[150:153], v[154:157], v[36:39]
	v_bitop3_b32 v154, v163, v194, v162 bitop3:0x36
	v_bitop3_b32 v155, v165, v194, v162 bitop3:0x36
	v_lshl_add_u32 v154, v154, 4, v164
	s_waitcnt lgkmcnt(0)
	v_mfma_f32_16x16x32_bf16 v[32:35], v[150:153], v[158:161], v[32:35]
	v_bitop3_b32 v158, v163, v195, v162 bitop3:0x36
	v_bitop3_b32 v159, v165, v195, v162 bitop3:0x36
	v_lshl_add_u32 v156, v155, 4, v149
	v_lshl_add_u32 v158, v158, 4, v164
	v_lshl_add_u32 v160, v159, 4, v149
	ds_read_b64_tr_b16 v[154:155], v154
	ds_read_b64_tr_b16 v[156:157], v156
	ds_read_b64_tr_b16 v[158:159], v158
	ds_read_b64_tr_b16 v[160:161], v160
	s_waitcnt lgkmcnt(2)
	v_mfma_f32_16x16x32_bf16 v[28:31], v[150:153], v[154:157], v[28:31]
	v_bitop3_b32 v154, v163, v196, v162 bitop3:0x36
	v_bitop3_b32 v155, v165, v196, v162 bitop3:0x36
	v_lshl_add_u32 v154, v154, 4, v164
	s_waitcnt lgkmcnt(0)
	v_mfma_f32_16x16x32_bf16 v[24:27], v[150:153], v[158:161], v[24:27]
	v_bitop3_b32 v158, v163, v197, v162 bitop3:0x36
	v_lshl_add_u32 v156, v155, 4, v149
	v_lshl_add_u32 v158, v158, 4, v164
	v_bitop3_b32 v159, v165, v197, v162 bitop3:0x36
	ds_read_b64_tr_b16 v[154:155], v154
	ds_read_b64_tr_b16 v[156:157], v156
	v_lshl_add_u32 v149, v159, 4, v149
	ds_read_b64_tr_b16 v[158:159], v158
	ds_read_b64_tr_b16 v[160:161], v149
	s_waitcnt lgkmcnt(2)
	v_mfma_f32_16x16x32_bf16 v[20:23], v[150:153], v[154:157], v[20:23]
	s_waitcnt lgkmcnt(0)
	s_add_u32 s52, s52, 0x20000
	s_waitcnt lgkmcnt(0)
	v_mfma_f32_16x16x32_bf16 v[16:19], v[150:153], v[158:161], v[16:19]
	s_addc_u32 s53, s53, 0
	s_cmp_eq_u32 s52, 0x80000
	v_add_u32_e32 v148, 64, v148
	v_lshl_add_u64 v[174:175], v[146:147], 0, s[52:53]
	v_add_co_u32_e32 v52, vcc, 0x20000, v174
	s_nop 1
	v_addc_co_u32_e32 v53, vcc, 0, v175, vcc
	global_load_dwordx4 v[52:55], v[52:53], off nt
	v_add_co_u32_e32 v56, vcc, 0x22000, v174
	s_nop 1
	v_addc_co_u32_e32 v57, vcc, 0, v175, vcc
	global_load_dwordx4 v[56:59], v[56:57], off nt
	v_add_co_u32_e32 v60, vcc, 0x24000, v174
	s_nop 1
	v_addc_co_u32_e32 v61, vcc, 0, v175, vcc
	global_load_dwordx4 v[60:63], v[60:61], off nt
	v_add_co_u32_e32 v64, vcc, 0x26000, v174
	s_nop 1
	v_addc_co_u32_e32 v65, vcc, 0, v175, vcc
	global_load_dwordx4 v[64:67], v[64:65], off nt
	v_add_co_u32_e32 v68, vcc, 0x28000, v174
	s_nop 1
	v_addc_co_u32_e32 v69, vcc, 0, v175, vcc
	global_load_dwordx4 v[68:71], v[68:69], off nt
	v_add_co_u32_e32 v72, vcc, 0x2a000, v174
	s_nop 1
	v_addc_co_u32_e32 v73, vcc, 0, v175, vcc
	global_load_dwordx4 v[72:75], v[72:73], off nt
	v_mov_b32_e32 v149, v121
	v_mov_b32_e32 v154, v117
	s_waitcnt vmcnt(21)
	v_cvt_pk_bf16_f32 v150, v166, v167
	v_add_u32_e32 v157, 2, v154
	v_lshlrev_b32_e32 v153, 2, v154
	v_lshlrev_b32_e32 v159, 2, v157
	v_and_b32_e32 v155, 12, v153
	v_bfe_u32 v153, v154, 2, 2
	v_lshlrev_b32_e32 v158, 8, v157
	v_and_b32_e32 v159, 12, v159
	v_bfe_u32 v157, v157, 2, 2
	v_bitop3_b32 v153, v155, v119, v153 bitop3:0x36
	v_bitop3_b32 v157, v159, v119, v157 bitop3:0x36
	v_lshlrev_b32_e32 v152, 8, v154
	v_lshl_add_u32 v153, v153, 4, s39
	v_lshl_add_u32 v157, v157, 4, s39
	v_add3_u32 v156, v153, v152, v123
	s_waitcnt vmcnt(20)
	v_cvt_pk_bf16_f32 v152, v170, v171
	v_cvt_pk_bf16_f32 v153, v172, v173
	v_add3_u32 v157, v157, v158, v123
	ds_write_b64 v157, v[152:153]
	v_add_u32_e32 v157, 4, v154
	v_lshlrev_b32_e32 v158, 8, v157
	v_bfe_u32 v157, v157, 2, 2
	v_bitop3_b32 v157, v157, v119, v155 bitop3:0x36
	v_lshl_add_u32 v157, v157, 4, s39
	s_waitcnt vmcnt(19)
	v_cvt_pk_bf16_f32 v152, v238, v239
	v_cvt_pk_bf16_f32 v153, v240, v241
	v_add3_u32 v157, v157, v158, v123
	ds_write_b64 v157, v[152:153]
	v_add_u32_e32 v157, 6, v154
	v_lshlrev_b32_e32 v159, 2, v157
	v_lshlrev_b32_e32 v158, 8, v157
	v_and_b32_e32 v159, 12, v159
	v_bfe_u32 v157, v157, 2, 2
	v_bitop3_b32 v157, v159, v119, v157 bitop3:0x36
	v_lshl_add_u32 v157, v157, 4, s39
	s_waitcnt vmcnt(18)
	v_cvt_pk_bf16_f32 v152, v242, v243
	v_cvt_pk_bf16_f32 v153, v244, v245
	v_add3_u32 v157, v157, v158, v123
	ds_write_b64 v157, v[152:153]
	v_add_u32_e32 v157, 8, v154
	v_lshlrev_b32_e32 v158, 8, v157
	v_bfe_u32 v157, v157, 2, 2
	v_bitop3_b32 v157, v157, v119, v155 bitop3:0x36
	v_lshl_add_u32 v157, v157, 4, s39
	s_waitcnt vmcnt(17)
	v_cvt_pk_bf16_f32 v152, v246, v247
	v_cvt_pk_bf16_f32 v153, v248, v249
	v_add3_u32 v157, v157, v158, v123
	ds_write_b64 v157, v[152:153]
	v_add_u32_e32 v157, 10, v154
	v_lshlrev_b32_e32 v159, 2, v157
	v_lshlrev_b32_e32 v158, 8, v157
	v_and_b32_e32 v159, 12, v159
	v_bfe_u32 v157, v157, 2, 2
	v_bitop3_b32 v157, v159, v119, v157 bitop3:0x36
	v_lshl_add_u32 v157, v157, 4, s39
	s_waitcnt vmcnt(16)
	v_cvt_pk_bf16_f32 v152, v250, v251
	v_cvt_pk_bf16_f32 v153, v252, v253
	v_add3_u32 v157, v157, v158, v123
	ds_write_b64 v157, v[152:153]
	v_add_u32_e32 v157, 12, v154
	v_lshlrev_b32_e32 v158, 8, v157
	v_bfe_u32 v157, v157, 2, 2
	v_bitop3_b32 v157, v157, v119, v155 bitop3:0x36
	v_lshl_add_u32 v157, v157, 4, s39
	s_waitcnt vmcnt(15)
	v_cvt_pk_bf16_f32 v152, v76, v77
	v_cvt_pk_bf16_f32 v153, v78, v79
	v_add3_u32 v157, v157, v158, v123
	ds_write_b64 v157, v[152:153]
	v_add_u32_e32 v157, 14, v154
	v_lshlrev_b32_e32 v159, 2, v157
	v_lshlrev_b32_e32 v158, 8, v157
	v_and_b32_e32 v159, 12, v159
	v_bfe_u32 v157, v157, 2, 2
	v_bitop3_b32 v157, v159, v119, v157 bitop3:0x36
	v_lshl_add_u32 v157, v157, 4, s39
	s_waitcnt vmcnt(14)
	v_cvt_pk_bf16_f32 v152, v80, v81
	v_cvt_pk_bf16_f32 v153, v82, v83
	v_add3_u32 v157, v157, v158, v123
	v_cvt_pk_bf16_f32 v151, v168, v169
	ds_write_b64 v157, v[152:153]
	s_waitcnt vmcnt(13)
	v_cvt_pk_bf16_f32 v152, v84, v85
	v_cvt_pk_bf16_f32 v153, v86, v87
	ds_write2st64_b64 v156, v[150:151], v[152:153] offset1:8
	v_add_u32_e32 v152, 18, v154
	v_lshlrev_b32_e32 v156, 2, v152
	v_lshlrev_b32_e32 v153, 8, v152
	v_and_b32_e32 v156, 12, v156
	v_bfe_u32 v152, v152, 2, 2
	v_bitop3_b32 v152, v156, v119, v152 bitop3:0x36
	v_lshl_add_u32 v152, v152, 4, s39
	s_waitcnt vmcnt(12)
	v_cvt_pk_bf16_f32 v150, v88, v89
	v_cvt_pk_bf16_f32 v151, v90, v91
	v_add3_u32 v152, v152, v153, v123
	ds_write_b64 v152, v[150:151]
	v_add_u32_e32 v152, 20, v154
	v_lshlrev_b32_e32 v153, 8, v152
	v_bfe_u32 v152, v152, 2, 2
	v_bitop3_b32 v152, v152, v119, v155 bitop3:0x36
	v_lshl_add_u32 v152, v152, 4, s39
	s_waitcnt vmcnt(11)
	v_cvt_pk_bf16_f32 v150, v92, v93
	v_cvt_pk_bf16_f32 v151, v94, v95
	v_add3_u32 v152, v152, v153, v123
	ds_write_b64 v152, v[150:151]
	v_add_u32_e32 v152, 22, v154
	v_lshlrev_b32_e32 v156, 2, v152
	v_lshlrev_b32_e32 v153, 8, v152
	v_and_b32_e32 v156, 12, v156
	v_bfe_u32 v152, v152, 2, 2
	v_bitop3_b32 v152, v156, v119, v152 bitop3:0x36
	v_lshl_add_u32 v152, v152, 4, s39
	s_waitcnt vmcnt(10)
	v_cvt_pk_bf16_f32 v150, v96, v97
	v_cvt_pk_bf16_f32 v151, v98, v99
	v_add3_u32 v152, v152, v153, v123
	ds_write_b64 v152, v[150:151]
	v_add_u32_e32 v152, 24, v154
	v_lshlrev_b32_e32 v153, 8, v152
	v_bfe_u32 v152, v152, 2, 2
	v_bitop3_b32 v152, v152, v119, v155 bitop3:0x36
	v_lshl_add_u32 v152, v152, 4, s39
	s_waitcnt vmcnt(9)
	v_cvt_pk_bf16_f32 v150, v100, v101
	v_cvt_pk_bf16_f32 v151, v102, v103
	v_add3_u32 v152, v152, v153, v123
	ds_write_b64 v152, v[150:151]
	v_add_u32_e32 v152, 26, v154
	v_lshlrev_b32_e32 v156, 2, v152
	v_lshlrev_b32_e32 v153, 8, v152
	v_and_b32_e32 v156, 12, v156
	v_bfe_u32 v152, v152, 2, 2
	v_bitop3_b32 v152, v156, v119, v152 bitop3:0x36
	v_lshl_add_u32 v152, v152, 4, s39
	s_waitcnt vmcnt(8)
	v_cvt_pk_bf16_f32 v150, v104, v105
	v_cvt_pk_bf16_f32 v151, v106, v107
	v_add3_u32 v152, v152, v153, v123
	ds_write_b64 v152, v[150:151]
	v_add_u32_e32 v152, 28, v154
	v_lshlrev_b32_e32 v153, 8, v152
	v_bfe_u32 v152, v152, 2, 2
	v_bitop3_b32 v152, v152, v119, v155 bitop3:0x36
	v_lshl_add_u32 v152, v152, 4, s39
	s_waitcnt vmcnt(7)
	v_cvt_pk_bf16_f32 v150, v108, v109
	v_cvt_pk_bf16_f32 v151, v110, v111
	v_add3_u32 v152, v152, v153, v123
	ds_write_b64 v152, v[150:151]
	v_add_u32_e32 v152, 30, v154
	v_lshlrev_b32_e32 v154, 2, v152
	v_lshlrev_b32_e32 v153, 8, v152
	v_and_b32_e32 v154, 12, v154
	v_bfe_u32 v152, v152, 2, 2
	v_bitop3_b32 v152, v154, v119, v152 bitop3:0x36
	v_lshl_add_u32 v152, v152, 4, s39
	s_waitcnt vmcnt(6)
	v_cvt_pk_bf16_f32 v150, v112, v113
	v_cvt_pk_bf16_f32 v151, v114, v115
	v_add3_u32 v152, v152, v153, v123
	ds_write_b64 v152, v[150:151]
	v_lshl_add_u64 v[108:109], v[146:147], 0, s[52:53]
	v_add_co_u32_e32 v76, vcc, 0x2c000, v108
	s_nop 1
	v_addc_co_u32_e32 v77, vcc, 0, v109, vcc
	global_load_dwordx4 v[76:79], v[76:77], off nt
	v_add_co_u32_e32 v80, vcc, 0x2e000, v108
	s_nop 1
	v_addc_co_u32_e32 v81, vcc, 0, v109, vcc
	global_load_dwordx4 v[80:83], v[80:81], off nt
	v_add_co_u32_e32 v84, vcc, 0x30000, v108
	s_nop 1
	v_addc_co_u32_e32 v85, vcc, 0, v109, vcc
	global_load_dwordx4 v[84:87], v[84:85], off nt
	v_add_co_u32_e32 v88, vcc, 0x32000, v108
	s_nop 1
	v_addc_co_u32_e32 v89, vcc, 0, v109, vcc
	global_load_dwordx4 v[88:91], v[88:89], off nt
	v_add_co_u32_e32 v92, vcc, 0x34000, v108
	s_nop 1
	v_addc_co_u32_e32 v93, vcc, 0, v109, vcc
	global_load_dwordx4 v[92:95], v[92:93], off nt
	v_add_co_u32_e32 v96, vcc, 0x36000, v108
	s_nop 1
	v_addc_co_u32_e32 v97, vcc, 0, v109, vcc
	global_load_dwordx4 v[96:99], v[96:97], off nt
	v_add_co_u32_e32 v100, vcc, 0x38000, v108
	s_nop 1
	v_addc_co_u32_e32 v101, vcc, 0, v109, vcc
	global_load_dwordx4 v[100:103], v[100:101], off nt
	v_add_co_u32_e32 v104, vcc, 0x3a000, v108
	s_nop 1
	v_addc_co_u32_e32 v105, vcc, 0, v109, vcc
	global_load_dwordx4 v[104:107], v[104:105], off nt
	v_add_co_u32_e32 v110, vcc, 0x3c000, v108
	s_nop 1
	v_addc_co_u32_e32 v111, vcc, 0, v109, vcc
	v_add_co_u32_e32 v112, vcc, 0x3e000, v108
	s_nop 1
	v_addc_co_u32_e32 v113, vcc, 0, v109, vcc
	global_load_dwordx4 v[108:111], v[110:111], off nt
	s_nop 0
	global_load_dwordx4 v[112:115], v[112:113], off nt
	s_waitcnt lgkmcnt(0)
	ds_read_b128 v[150:153], v148
	v_add_u32_e32 v154, v149, v120
	v_lshlrev_b32_e32 v155, 2, v149
	v_add_u32_e32 v149, v149, v183
	v_and_b32_e32 v162, 12, v155
	v_bfe_u32 v163, v154, 2, 2
	v_bfe_u32 v165, v149, 2, 2
	v_lshl_add_u32 v164, v154, 8, v182
	v_lshl_add_u32 v149, v149, 8, v182
	v_bitop3_b32 v154, v163, v181, v162 bitop3:0x36
	v_bitop3_b32 v155, v165, v181, v162 bitop3:0x36
	v_bitop3_b32 v158, v163, v191, v162 bitop3:0x36
	v_bitop3_b32 v159, v165, v191, v162 bitop3:0x36
	v_lshl_add_u32 v154, v154, 4, v164
	v_lshl_add_u32 v156, v155, 4, v149
	v_lshl_add_u32 v158, v158, 4, v164
	v_lshl_add_u32 v160, v159, 4, v149
	ds_read_b64_tr_b16 v[154:155], v154
	ds_read_b64_tr_b16 v[156:157], v156
	ds_read_b64_tr_b16 v[158:159], v158
	ds_read_b64_tr_b16 v[160:161], v160
	s_waitcnt lgkmcnt(2)
	v_mfma_f32_16x16x32_bf16 v[44:47], v[150:153], v[154:157], v[44:47]
	v_bitop3_b32 v154, v163, v192, v162 bitop3:0x36
	v_bitop3_b32 v155, v165, v192, v162 bitop3:0x36
	v_lshl_add_u32 v154, v154, 4, v164
	s_waitcnt lgkmcnt(0)
	v_mfma_f32_16x16x32_bf16 v[40:43], v[150:153], v[158:161], v[40:43]
	v_bitop3_b32 v158, v163, v193, v162 bitop3:0x36
	v_bitop3_b32 v159, v165, v193, v162 bitop3:0x36
	v_lshl_add_u32 v156, v155, 4, v149
	v_lshl_add_u32 v158, v158, 4, v164
	v_lshl_add_u32 v160, v159, 4, v149
	ds_read_b64_tr_b16 v[154:155], v154
	ds_read_b64_tr_b16 v[156:157], v156
	ds_read_b64_tr_b16 v[158:159], v158
	ds_read_b64_tr_b16 v[160:161], v160
	s_waitcnt lgkmcnt(2)
	v_mfma_f32_16x16x32_bf16 v[36:39], v[150:153], v[154:157], v[36:39]
	v_bitop3_b32 v154, v163, v194, v162 bitop3:0x36
	v_bitop3_b32 v155, v165, v194, v162 bitop3:0x36
	v_lshl_add_u32 v154, v154, 4, v164
	s_waitcnt lgkmcnt(0)
	v_mfma_f32_16x16x32_bf16 v[32:35], v[150:153], v[158:161], v[32:35]
	v_bitop3_b32 v158, v163, v195, v162 bitop3:0x36
	v_bitop3_b32 v159, v165, v195, v162 bitop3:0x36
	v_lshl_add_u32 v156, v155, 4, v149
	v_lshl_add_u32 v158, v158, 4, v164
	v_lshl_add_u32 v160, v159, 4, v149
	ds_read_b64_tr_b16 v[154:155], v154
	ds_read_b64_tr_b16 v[156:157], v156
	ds_read_b64_tr_b16 v[158:159], v158
	ds_read_b64_tr_b16 v[160:161], v160
	s_waitcnt lgkmcnt(2)
	v_mfma_f32_16x16x32_bf16 v[28:31], v[150:153], v[154:157], v[28:31]
	v_bitop3_b32 v154, v163, v196, v162 bitop3:0x36
	v_bitop3_b32 v155, v165, v196, v162 bitop3:0x36
	v_lshl_add_u32 v154, v154, 4, v164
	s_waitcnt lgkmcnt(0)
	v_mfma_f32_16x16x32_bf16 v[24:27], v[150:153], v[158:161], v[24:27]
	v_bitop3_b32 v158, v163, v197, v162 bitop3:0x36
	v_lshl_add_u32 v156, v155, 4, v149
	v_lshl_add_u32 v158, v158, 4, v164
	v_bitop3_b32 v159, v165, v197, v162 bitop3:0x36
	ds_read_b64_tr_b16 v[154:155], v154
	ds_read_b64_tr_b16 v[156:157], v156
	v_lshl_add_u32 v149, v159, 4, v149
	ds_read_b64_tr_b16 v[158:159], v158
	ds_read_b64_tr_b16 v[160:161], v149
	s_waitcnt lgkmcnt(2)
	v_mfma_f32_16x16x32_bf16 v[20:23], v[150:153], v[154:157], v[20:23]
	s_waitcnt lgkmcnt(0)
	s_add_u32 s52, s52, 0x20000
	s_waitcnt lgkmcnt(0)
	v_mfma_f32_16x16x32_bf16 v[16:19], v[150:153], v[158:161], v[16:19]
	s_addc_u32 s53, s53, 0
	s_cmp_eq_u32 s52, 0x80000
	v_add_u32_e32 v148, 64, v148
	v_lshl_add_u64 v[174:175], v[146:147], 0, s[52:53]
	v_add_co_u32_e32 v166, vcc, 0x20000, v174
	s_nop 1
	v_addc_co_u32_e32 v167, vcc, 0, v175, vcc
	global_load_dwordx4 v[166:169], v[166:167], off nt
	v_add_co_u32_e32 v170, vcc, 0x22000, v174
	s_nop 1
	v_addc_co_u32_e32 v171, vcc, 0, v175, vcc
	global_load_dwordx4 v[170:173], v[170:171], off nt
	v_add_co_u32_e32 v238, vcc, 0x24000, v174
	s_nop 1
	v_addc_co_u32_e32 v239, vcc, 0, v175, vcc
	global_load_dwordx4 v[238:241], v[238:239], off nt
	v_add_co_u32_e32 v242, vcc, 0x26000, v174
	s_nop 1
	v_addc_co_u32_e32 v243, vcc, 0, v175, vcc
	global_load_dwordx4 v[242:245], v[242:243], off nt
	v_add_co_u32_e32 v246, vcc, 0x28000, v174
	s_nop 1
	v_addc_co_u32_e32 v247, vcc, 0, v175, vcc
	global_load_dwordx4 v[246:249], v[246:247], off nt
	v_add_co_u32_e32 v250, vcc, 0x2a000, v174
	s_nop 1
	v_addc_co_u32_e32 v251, vcc, 0, v175, vcc
	global_load_dwordx4 v[250:253], v[250:251], off nt
	v_mov_b32_e32 v149, v121
	v_mov_b32_e32 v154, v117
	s_waitcnt vmcnt(21)
	v_cvt_pk_bf16_f32 v150, v52, v53
	v_add_u32_e32 v157, 2, v154
	v_lshlrev_b32_e32 v153, 2, v154
	v_lshlrev_b32_e32 v159, 2, v157
	v_and_b32_e32 v155, 12, v153
	v_bfe_u32 v153, v154, 2, 2
	v_lshlrev_b32_e32 v158, 8, v157
	v_and_b32_e32 v159, 12, v159
	v_bfe_u32 v157, v157, 2, 2
	v_bitop3_b32 v153, v155, v119, v153 bitop3:0x36
	v_bitop3_b32 v157, v159, v119, v157 bitop3:0x36
	v_lshlrev_b32_e32 v152, 8, v154
	v_lshl_add_u32 v153, v153, 4, s39
	v_lshl_add_u32 v157, v157, 4, s39
	v_add3_u32 v156, v153, v152, v123
	s_waitcnt vmcnt(20)
	v_cvt_pk_bf16_f32 v152, v56, v57
	v_cvt_pk_bf16_f32 v153, v58, v59
	v_add3_u32 v157, v157, v158, v123
	ds_write_b64 v157, v[152:153]
	v_add_u32_e32 v157, 4, v154
	v_lshlrev_b32_e32 v158, 8, v157
	v_bfe_u32 v157, v157, 2, 2
	v_bitop3_b32 v157, v157, v119, v155 bitop3:0x36
	v_lshl_add_u32 v157, v157, 4, s39
	s_waitcnt vmcnt(19)
	v_cvt_pk_bf16_f32 v152, v60, v61
	v_cvt_pk_bf16_f32 v153, v62, v63
	v_add3_u32 v157, v157, v158, v123
	ds_write_b64 v157, v[152:153]
	v_add_u32_e32 v157, 6, v154
	v_lshlrev_b32_e32 v159, 2, v157
	v_lshlrev_b32_e32 v158, 8, v157
	v_and_b32_e32 v159, 12, v159
	v_bfe_u32 v157, v157, 2, 2
	v_bitop3_b32 v157, v159, v119, v157 bitop3:0x36
	v_lshl_add_u32 v157, v157, 4, s39
	s_waitcnt vmcnt(18)
	v_cvt_pk_bf16_f32 v152, v64, v65
	v_cvt_pk_bf16_f32 v153, v66, v67
	v_add3_u32 v157, v157, v158, v123
	ds_write_b64 v157, v[152:153]
	v_add_u32_e32 v157, 8, v154
	v_lshlrev_b32_e32 v158, 8, v157
	v_bfe_u32 v157, v157, 2, 2
	v_bitop3_b32 v157, v157, v119, v155 bitop3:0x36
	v_lshl_add_u32 v157, v157, 4, s39
	s_waitcnt vmcnt(17)
	v_cvt_pk_bf16_f32 v152, v68, v69
	v_cvt_pk_bf16_f32 v153, v70, v71
	v_add3_u32 v157, v157, v158, v123
	ds_write_b64 v157, v[152:153]
	v_add_u32_e32 v157, 10, v154
	v_lshlrev_b32_e32 v159, 2, v157
	v_lshlrev_b32_e32 v158, 8, v157
	v_and_b32_e32 v159, 12, v159
	v_bfe_u32 v157, v157, 2, 2
	v_bitop3_b32 v157, v159, v119, v157 bitop3:0x36
	v_lshl_add_u32 v157, v157, 4, s39
	s_waitcnt vmcnt(16)
	v_cvt_pk_bf16_f32 v152, v72, v73
	v_cvt_pk_bf16_f32 v153, v74, v75
	v_add3_u32 v157, v157, v158, v123
	ds_write_b64 v157, v[152:153]
	v_add_u32_e32 v157, 12, v154
	v_lshlrev_b32_e32 v158, 8, v157
	v_bfe_u32 v157, v157, 2, 2
	v_bitop3_b32 v157, v157, v119, v155 bitop3:0x36
	v_lshl_add_u32 v157, v157, 4, s39
	s_waitcnt vmcnt(15)
	v_cvt_pk_bf16_f32 v152, v76, v77
	v_cvt_pk_bf16_f32 v153, v78, v79
	v_add3_u32 v157, v157, v158, v123
	ds_write_b64 v157, v[152:153]
	v_add_u32_e32 v157, 14, v154
	v_lshlrev_b32_e32 v159, 2, v157
	v_lshlrev_b32_e32 v158, 8, v157
	v_and_b32_e32 v159, 12, v159
	v_bfe_u32 v157, v157, 2, 2
	v_bitop3_b32 v157, v159, v119, v157 bitop3:0x36
	v_lshl_add_u32 v157, v157, 4, s39
	s_waitcnt vmcnt(14)
	v_cvt_pk_bf16_f32 v152, v80, v81
	v_cvt_pk_bf16_f32 v153, v82, v83
	v_add3_u32 v157, v157, v158, v123
	v_cvt_pk_bf16_f32 v151, v54, v55
	ds_write_b64 v157, v[152:153]
	s_waitcnt vmcnt(13)
	v_cvt_pk_bf16_f32 v152, v84, v85
	v_cvt_pk_bf16_f32 v153, v86, v87
	ds_write2st64_b64 v156, v[150:151], v[152:153] offset1:8
	v_add_u32_e32 v152, 18, v154
	v_lshlrev_b32_e32 v156, 2, v152
	v_lshlrev_b32_e32 v153, 8, v152
	v_and_b32_e32 v156, 12, v156
	v_bfe_u32 v152, v152, 2, 2
	v_bitop3_b32 v152, v156, v119, v152 bitop3:0x36
	v_lshl_add_u32 v152, v152, 4, s39
	s_waitcnt vmcnt(12)
	v_cvt_pk_bf16_f32 v150, v88, v89
	v_cvt_pk_bf16_f32 v151, v90, v91
	v_add3_u32 v152, v152, v153, v123
	ds_write_b64 v152, v[150:151]
	v_add_u32_e32 v152, 20, v154
	v_lshlrev_b32_e32 v153, 8, v152
	v_bfe_u32 v152, v152, 2, 2
	v_bitop3_b32 v152, v152, v119, v155 bitop3:0x36
	v_lshl_add_u32 v152, v152, 4, s39
	s_waitcnt vmcnt(11)
	v_cvt_pk_bf16_f32 v150, v92, v93
	v_cvt_pk_bf16_f32 v151, v94, v95
	v_add3_u32 v152, v152, v153, v123
	ds_write_b64 v152, v[150:151]
	v_add_u32_e32 v152, 22, v154
	v_lshlrev_b32_e32 v156, 2, v152
	v_lshlrev_b32_e32 v153, 8, v152
	v_and_b32_e32 v156, 12, v156
	v_bfe_u32 v152, v152, 2, 2
	v_bitop3_b32 v152, v156, v119, v152 bitop3:0x36
	v_lshl_add_u32 v152, v152, 4, s39
	s_waitcnt vmcnt(10)
	v_cvt_pk_bf16_f32 v150, v96, v97
	v_cvt_pk_bf16_f32 v151, v98, v99
	v_add3_u32 v152, v152, v153, v123
	ds_write_b64 v152, v[150:151]
	v_add_u32_e32 v152, 24, v154
	v_lshlrev_b32_e32 v153, 8, v152
	v_bfe_u32 v152, v152, 2, 2
	v_bitop3_b32 v152, v152, v119, v155 bitop3:0x36
	v_lshl_add_u32 v152, v152, 4, s39
	s_waitcnt vmcnt(9)
	v_cvt_pk_bf16_f32 v150, v100, v101
	v_cvt_pk_bf16_f32 v151, v102, v103
	v_add3_u32 v152, v152, v153, v123
	ds_write_b64 v152, v[150:151]
	v_add_u32_e32 v152, 26, v154
	v_lshlrev_b32_e32 v156, 2, v152
	v_lshlrev_b32_e32 v153, 8, v152
	v_and_b32_e32 v156, 12, v156
	v_bfe_u32 v152, v152, 2, 2
	v_bitop3_b32 v152, v156, v119, v152 bitop3:0x36
	v_lshl_add_u32 v152, v152, 4, s39
	s_waitcnt vmcnt(8)
	v_cvt_pk_bf16_f32 v150, v104, v105
	v_cvt_pk_bf16_f32 v151, v106, v107
	v_add3_u32 v152, v152, v153, v123
	ds_write_b64 v152, v[150:151]
	v_add_u32_e32 v152, 28, v154
	v_lshlrev_b32_e32 v153, 8, v152
	v_bfe_u32 v152, v152, 2, 2
	v_bitop3_b32 v152, v152, v119, v155 bitop3:0x36
	v_lshl_add_u32 v152, v152, 4, s39
	s_waitcnt vmcnt(7)
	v_cvt_pk_bf16_f32 v150, v108, v109
	v_cvt_pk_bf16_f32 v151, v110, v111
	v_add3_u32 v152, v152, v153, v123
	ds_write_b64 v152, v[150:151]
	v_add_u32_e32 v152, 30, v154
	v_lshlrev_b32_e32 v154, 2, v152
	v_lshlrev_b32_e32 v153, 8, v152
	v_and_b32_e32 v154, 12, v154
	v_bfe_u32 v152, v152, 2, 2
	v_bitop3_b32 v152, v154, v119, v152 bitop3:0x36
	v_lshl_add_u32 v152, v152, 4, s39
	s_waitcnt vmcnt(6)
	v_cvt_pk_bf16_f32 v150, v112, v113
	v_cvt_pk_bf16_f32 v151, v114, v115
	v_add3_u32 v152, v152, v153, v123
	ds_write_b64 v152, v[150:151]
	v_lshl_add_u64 v[108:109], v[146:147], 0, s[52:53]
	v_add_co_u32_e32 v76, vcc, 0x2c000, v108
	s_nop 1
	v_addc_co_u32_e32 v77, vcc, 0, v109, vcc
	global_load_dwordx4 v[76:79], v[76:77], off nt
	v_add_co_u32_e32 v80, vcc, 0x2e000, v108
	s_nop 1
	v_addc_co_u32_e32 v81, vcc, 0, v109, vcc
	global_load_dwordx4 v[80:83], v[80:81], off nt
	v_add_co_u32_e32 v84, vcc, 0x30000, v108
	s_nop 1
	v_addc_co_u32_e32 v85, vcc, 0, v109, vcc
	global_load_dwordx4 v[84:87], v[84:85], off nt
	v_add_co_u32_e32 v88, vcc, 0x32000, v108
	s_nop 1
	v_addc_co_u32_e32 v89, vcc, 0, v109, vcc
	global_load_dwordx4 v[88:91], v[88:89], off nt
	v_add_co_u32_e32 v92, vcc, 0x34000, v108
	s_nop 1
	v_addc_co_u32_e32 v93, vcc, 0, v109, vcc
	global_load_dwordx4 v[92:95], v[92:93], off nt
	v_add_co_u32_e32 v96, vcc, 0x36000, v108
	s_nop 1
	v_addc_co_u32_e32 v97, vcc, 0, v109, vcc
	global_load_dwordx4 v[96:99], v[96:97], off nt
	v_add_co_u32_e32 v100, vcc, 0x38000, v108
	s_nop 1
	v_addc_co_u32_e32 v101, vcc, 0, v109, vcc
	global_load_dwordx4 v[100:103], v[100:101], off nt
	v_add_co_u32_e32 v104, vcc, 0x3a000, v108
	s_nop 1
	v_addc_co_u32_e32 v105, vcc, 0, v109, vcc
	global_load_dwordx4 v[104:107], v[104:105], off nt
	v_add_co_u32_e32 v110, vcc, 0x3c000, v108
	s_nop 1
	v_addc_co_u32_e32 v111, vcc, 0, v109, vcc
	v_add_co_u32_e32 v112, vcc, 0x3e000, v108
	s_nop 1
	v_addc_co_u32_e32 v113, vcc, 0, v109, vcc
	global_load_dwordx4 v[108:111], v[110:111], off nt
	s_nop 0
	global_load_dwordx4 v[112:115], v[112:113], off nt
	s_waitcnt lgkmcnt(0)
	ds_read_b128 v[150:153], v148
	v_add_u32_e32 v154, v149, v120
	v_lshlrev_b32_e32 v155, 2, v149
	v_add_u32_e32 v149, v149, v183
	v_and_b32_e32 v162, 12, v155
	v_bfe_u32 v163, v154, 2, 2
	v_bfe_u32 v165, v149, 2, 2
	v_lshl_add_u32 v164, v154, 8, v182
	v_lshl_add_u32 v149, v149, 8, v182
	v_bitop3_b32 v154, v163, v181, v162 bitop3:0x36
	v_bitop3_b32 v155, v165, v181, v162 bitop3:0x36
	v_bitop3_b32 v158, v163, v191, v162 bitop3:0x36
	v_bitop3_b32 v159, v165, v191, v162 bitop3:0x36
	v_lshl_add_u32 v154, v154, 4, v164
	v_lshl_add_u32 v156, v155, 4, v149
	v_lshl_add_u32 v158, v158, 4, v164
	v_lshl_add_u32 v160, v159, 4, v149
	ds_read_b64_tr_b16 v[154:155], v154
	ds_read_b64_tr_b16 v[156:157], v156
	ds_read_b64_tr_b16 v[158:159], v158
	ds_read_b64_tr_b16 v[160:161], v160
	s_waitcnt lgkmcnt(2)
	v_mfma_f32_16x16x32_bf16 v[44:47], v[150:153], v[154:157], v[44:47]
	v_bitop3_b32 v154, v163, v192, v162 bitop3:0x36
	v_bitop3_b32 v155, v165, v192, v162 bitop3:0x36
	v_lshl_add_u32 v154, v154, 4, v164
	s_waitcnt lgkmcnt(0)
	v_mfma_f32_16x16x32_bf16 v[40:43], v[150:153], v[158:161], v[40:43]
	v_bitop3_b32 v158, v163, v193, v162 bitop3:0x36
	v_bitop3_b32 v159, v165, v193, v162 bitop3:0x36
	v_lshl_add_u32 v156, v155, 4, v149
	v_lshl_add_u32 v158, v158, 4, v164
	v_lshl_add_u32 v160, v159, 4, v149
	ds_read_b64_tr_b16 v[154:155], v154
	ds_read_b64_tr_b16 v[156:157], v156
	ds_read_b64_tr_b16 v[158:159], v158
	ds_read_b64_tr_b16 v[160:161], v160
	s_waitcnt lgkmcnt(2)
	v_mfma_f32_16x16x32_bf16 v[36:39], v[150:153], v[154:157], v[36:39]
	v_bitop3_b32 v154, v163, v194, v162 bitop3:0x36
	v_bitop3_b32 v155, v165, v194, v162 bitop3:0x36
	v_lshl_add_u32 v154, v154, 4, v164
	s_waitcnt lgkmcnt(0)
	v_mfma_f32_16x16x32_bf16 v[32:35], v[150:153], v[158:161], v[32:35]
	v_bitop3_b32 v158, v163, v195, v162 bitop3:0x36
	v_bitop3_b32 v159, v165, v195, v162 bitop3:0x36
	v_lshl_add_u32 v156, v155, 4, v149
	v_lshl_add_u32 v158, v158, 4, v164
	v_lshl_add_u32 v160, v159, 4, v149
	ds_read_b64_tr_b16 v[154:155], v154
	ds_read_b64_tr_b16 v[156:157], v156
	ds_read_b64_tr_b16 v[158:159], v158
	ds_read_b64_tr_b16 v[160:161], v160
	s_waitcnt lgkmcnt(2)
	v_mfma_f32_16x16x32_bf16 v[28:31], v[150:153], v[154:157], v[28:31]
	v_bitop3_b32 v154, v163, v196, v162 bitop3:0x36
	v_bitop3_b32 v155, v165, v196, v162 bitop3:0x36
	v_lshl_add_u32 v154, v154, 4, v164
	s_waitcnt lgkmcnt(0)
	v_mfma_f32_16x16x32_bf16 v[24:27], v[150:153], v[158:161], v[24:27]
	v_bitop3_b32 v158, v163, v197, v162 bitop3:0x36
	v_lshl_add_u32 v156, v155, 4, v149
	v_lshl_add_u32 v158, v158, 4, v164
	v_bitop3_b32 v159, v165, v197, v162 bitop3:0x36
	ds_read_b64_tr_b16 v[154:155], v154
	ds_read_b64_tr_b16 v[156:157], v156
	v_lshl_add_u32 v149, v159, 4, v149
	ds_read_b64_tr_b16 v[158:159], v158
	ds_read_b64_tr_b16 v[160:161], v149
	s_waitcnt lgkmcnt(2)
	v_mfma_f32_16x16x32_bf16 v[20:23], v[150:153], v[154:157], v[20:23]
	s_waitcnt lgkmcnt(0)
	s_add_u32 s52, s52, 0x20000
	s_waitcnt lgkmcnt(0)
	v_mfma_f32_16x16x32_bf16 v[16:19], v[150:153], v[158:161], v[16:19]
	s_addc_u32 s53, s53, 0
	s_cmp_eq_u32 s52, 0x80000
	v_add_u32_e32 v148, 64, v148
	v_mov_b32_e32 v149, v121
	v_mov_b32_e32 v154, v117
	s_waitcnt vmcnt(15)
	v_cvt_pk_bf16_f32 v150, v166, v167
	v_add_u32_e32 v157, 2, v154
	v_lshlrev_b32_e32 v153, 2, v154
	v_lshlrev_b32_e32 v159, 2, v157
	v_and_b32_e32 v155, 12, v153
	v_bfe_u32 v153, v154, 2, 2
	v_lshlrev_b32_e32 v158, 8, v157
	v_and_b32_e32 v159, 12, v159
	v_bfe_u32 v157, v157, 2, 2
	v_bitop3_b32 v153, v155, v119, v153 bitop3:0x36
	v_bitop3_b32 v157, v159, v119, v157 bitop3:0x36
	v_lshlrev_b32_e32 v152, 8, v154
	v_lshl_add_u32 v153, v153, 4, s39
	v_lshl_add_u32 v157, v157, 4, s39
	v_add3_u32 v156, v153, v152, v123
	s_waitcnt vmcnt(14)
	v_cvt_pk_bf16_f32 v152, v170, v171
	v_cvt_pk_bf16_f32 v153, v172, v173
	v_add3_u32 v157, v157, v158, v123
	ds_write_b64 v157, v[152:153]
	v_add_u32_e32 v157, 4, v154
	v_lshlrev_b32_e32 v158, 8, v157
	v_bfe_u32 v157, v157, 2, 2
	v_bitop3_b32 v157, v157, v119, v155 bitop3:0x36
	v_lshl_add_u32 v157, v157, 4, s39
	s_waitcnt vmcnt(13)
	v_cvt_pk_bf16_f32 v152, v238, v239
	v_cvt_pk_bf16_f32 v153, v240, v241
	v_add3_u32 v157, v157, v158, v123
	ds_write_b64 v157, v[152:153]
	v_add_u32_e32 v157, 6, v154
	v_lshlrev_b32_e32 v159, 2, v157
	v_lshlrev_b32_e32 v158, 8, v157
	v_and_b32_e32 v159, 12, v159
	v_bfe_u32 v157, v157, 2, 2
	v_bitop3_b32 v157, v159, v119, v157 bitop3:0x36
	v_lshl_add_u32 v157, v157, 4, s39
	s_waitcnt vmcnt(12)
	v_cvt_pk_bf16_f32 v152, v242, v243
	v_cvt_pk_bf16_f32 v153, v244, v245
	v_add3_u32 v157, v157, v158, v123
	ds_write_b64 v157, v[152:153]
	v_add_u32_e32 v157, 8, v154
	v_lshlrev_b32_e32 v158, 8, v157
	v_bfe_u32 v157, v157, 2, 2
	v_bitop3_b32 v157, v157, v119, v155 bitop3:0x36
	v_lshl_add_u32 v157, v157, 4, s39
	s_waitcnt vmcnt(11)
	v_cvt_pk_bf16_f32 v152, v246, v247
	v_cvt_pk_bf16_f32 v153, v248, v249
	v_add3_u32 v157, v157, v158, v123
	ds_write_b64 v157, v[152:153]
	v_add_u32_e32 v157, 10, v154
	v_lshlrev_b32_e32 v159, 2, v157
	v_lshlrev_b32_e32 v158, 8, v157
	v_and_b32_e32 v159, 12, v159
	v_bfe_u32 v157, v157, 2, 2
	v_bitop3_b32 v157, v159, v119, v157 bitop3:0x36
	v_lshl_add_u32 v157, v157, 4, s39
	s_waitcnt vmcnt(10)
	v_cvt_pk_bf16_f32 v152, v250, v251
	v_cvt_pk_bf16_f32 v153, v252, v253
	v_add3_u32 v157, v157, v158, v123
	ds_write_b64 v157, v[152:153]
	v_add_u32_e32 v157, 12, v154
	v_lshlrev_b32_e32 v158, 8, v157
	v_bfe_u32 v157, v157, 2, 2
	v_bitop3_b32 v157, v157, v119, v155 bitop3:0x36
	v_lshl_add_u32 v157, v157, 4, s39
	s_waitcnt vmcnt(9)
	v_cvt_pk_bf16_f32 v152, v76, v77
	v_cvt_pk_bf16_f32 v153, v78, v79
	v_add3_u32 v157, v157, v158, v123
	ds_write_b64 v157, v[152:153]
	v_add_u32_e32 v157, 14, v154
	v_lshlrev_b32_e32 v159, 2, v157
	v_lshlrev_b32_e32 v158, 8, v157
	v_and_b32_e32 v159, 12, v159
	v_bfe_u32 v157, v157, 2, 2
	v_bitop3_b32 v157, v159, v119, v157 bitop3:0x36
	v_lshl_add_u32 v157, v157, 4, s39
	s_waitcnt vmcnt(8)
	v_cvt_pk_bf16_f32 v152, v80, v81
	v_cvt_pk_bf16_f32 v153, v82, v83
	v_add3_u32 v157, v157, v158, v123
	v_cvt_pk_bf16_f32 v151, v168, v169
	ds_write_b64 v157, v[152:153]
	s_waitcnt vmcnt(7)
	v_cvt_pk_bf16_f32 v152, v84, v85
	v_cvt_pk_bf16_f32 v153, v86, v87
	ds_write2st64_b64 v156, v[150:151], v[152:153] offset1:8
	v_add_u32_e32 v152, 18, v154
	v_lshlrev_b32_e32 v156, 2, v152
	v_lshlrev_b32_e32 v153, 8, v152
	v_and_b32_e32 v156, 12, v156
	v_bfe_u32 v152, v152, 2, 2
	v_bitop3_b32 v152, v156, v119, v152 bitop3:0x36
	v_lshl_add_u32 v152, v152, 4, s39
	s_waitcnt vmcnt(6)
	v_cvt_pk_bf16_f32 v150, v88, v89
	v_cvt_pk_bf16_f32 v151, v90, v91
	v_add3_u32 v152, v152, v153, v123
	ds_write_b64 v152, v[150:151]
	v_add_u32_e32 v152, 20, v154
	v_lshlrev_b32_e32 v153, 8, v152
	v_bfe_u32 v152, v152, 2, 2
	v_bitop3_b32 v152, v152, v119, v155 bitop3:0x36
	v_lshl_add_u32 v152, v152, 4, s39
	s_waitcnt vmcnt(5)
	v_cvt_pk_bf16_f32 v150, v92, v93
	v_cvt_pk_bf16_f32 v151, v94, v95
	v_add3_u32 v152, v152, v153, v123
	ds_write_b64 v152, v[150:151]
	v_add_u32_e32 v152, 22, v154
	v_lshlrev_b32_e32 v156, 2, v152
	v_lshlrev_b32_e32 v153, 8, v152
	v_and_b32_e32 v156, 12, v156
	v_bfe_u32 v152, v152, 2, 2
	v_bitop3_b32 v152, v156, v119, v152 bitop3:0x36
	v_lshl_add_u32 v152, v152, 4, s39
	s_waitcnt vmcnt(4)
	v_cvt_pk_bf16_f32 v150, v96, v97
	v_cvt_pk_bf16_f32 v151, v98, v99
	v_add3_u32 v152, v152, v153, v123
	ds_write_b64 v152, v[150:151]
	v_add_u32_e32 v152, 24, v154
	v_lshlrev_b32_e32 v153, 8, v152
	v_bfe_u32 v152, v152, 2, 2
	v_bitop3_b32 v152, v152, v119, v155 bitop3:0x36
	v_lshl_add_u32 v152, v152, 4, s39
	s_waitcnt vmcnt(3)
	v_cvt_pk_bf16_f32 v150, v100, v101
	v_cvt_pk_bf16_f32 v151, v102, v103
	v_add3_u32 v152, v152, v153, v123
	ds_write_b64 v152, v[150:151]
	v_add_u32_e32 v152, 26, v154
	v_lshlrev_b32_e32 v156, 2, v152
	v_lshlrev_b32_e32 v153, 8, v152
	v_and_b32_e32 v156, 12, v156
	v_bfe_u32 v152, v152, 2, 2
	v_bitop3_b32 v152, v156, v119, v152 bitop3:0x36
	v_lshl_add_u32 v152, v152, 4, s39
	s_waitcnt vmcnt(2)
	v_cvt_pk_bf16_f32 v150, v104, v105
	v_cvt_pk_bf16_f32 v151, v106, v107
	v_add3_u32 v152, v152, v153, v123
	ds_write_b64 v152, v[150:151]
	v_add_u32_e32 v152, 28, v154
	v_lshlrev_b32_e32 v153, 8, v152
	v_bfe_u32 v152, v152, 2, 2
	v_bitop3_b32 v152, v152, v119, v155 bitop3:0x36
	v_lshl_add_u32 v152, v152, 4, s39
	s_waitcnt vmcnt(1)
	v_cvt_pk_bf16_f32 v150, v108, v109
	v_cvt_pk_bf16_f32 v151, v110, v111
	v_add3_u32 v152, v152, v153, v123
	ds_write_b64 v152, v[150:151]
	v_add_u32_e32 v152, 30, v154
	v_lshlrev_b32_e32 v154, 2, v152
	v_lshlrev_b32_e32 v153, 8, v152
	v_and_b32_e32 v154, 12, v154
	v_bfe_u32 v152, v152, 2, 2
	v_bitop3_b32 v152, v154, v119, v152 bitop3:0x36
	v_lshl_add_u32 v152, v152, 4, s39
	s_waitcnt vmcnt(0)
	v_cvt_pk_bf16_f32 v150, v112, v113
	v_cvt_pk_bf16_f32 v151, v114, v115
	v_add3_u32 v152, v152, v153, v123
	ds_write_b64 v152, v[150:151]
	s_waitcnt lgkmcnt(0)
	ds_read_b128 v[150:153], v148
	v_add_u32_e32 v154, v149, v120
	v_lshlrev_b32_e32 v155, 2, v149
	v_add_u32_e32 v149, v149, v183
	v_and_b32_e32 v162, 12, v155
	v_bfe_u32 v163, v154, 2, 2
	v_bfe_u32 v165, v149, 2, 2
	v_lshl_add_u32 v164, v154, 8, v182
	v_lshl_add_u32 v149, v149, 8, v182
	v_bitop3_b32 v154, v163, v181, v162 bitop3:0x36
	v_bitop3_b32 v155, v165, v181, v162 bitop3:0x36
	v_bitop3_b32 v158, v163, v191, v162 bitop3:0x36
	v_bitop3_b32 v159, v165, v191, v162 bitop3:0x36
	v_lshl_add_u32 v154, v154, 4, v164
	v_lshl_add_u32 v156, v155, 4, v149
	v_lshl_add_u32 v158, v158, 4, v164
	v_lshl_add_u32 v160, v159, 4, v149
	ds_read_b64_tr_b16 v[154:155], v154
	ds_read_b64_tr_b16 v[156:157], v156
	ds_read_b64_tr_b16 v[158:159], v158
	ds_read_b64_tr_b16 v[160:161], v160
	s_waitcnt lgkmcnt(2)
	v_mfma_f32_16x16x32_bf16 v[44:47], v[150:153], v[154:157], v[44:47]
	v_bitop3_b32 v154, v163, v192, v162 bitop3:0x36
	v_bitop3_b32 v155, v165, v192, v162 bitop3:0x36
	v_lshl_add_u32 v154, v154, 4, v164
	s_waitcnt lgkmcnt(0)
	v_mfma_f32_16x16x32_bf16 v[40:43], v[150:153], v[158:161], v[40:43]
	v_bitop3_b32 v158, v163, v193, v162 bitop3:0x36
	v_bitop3_b32 v159, v165, v193, v162 bitop3:0x36
	v_lshl_add_u32 v156, v155, 4, v149
	v_lshl_add_u32 v158, v158, 4, v164
	v_lshl_add_u32 v160, v159, 4, v149
	ds_read_b64_tr_b16 v[154:155], v154
	ds_read_b64_tr_b16 v[156:157], v156
	ds_read_b64_tr_b16 v[158:159], v158
	ds_read_b64_tr_b16 v[160:161], v160
	s_waitcnt lgkmcnt(2)
	v_mfma_f32_16x16x32_bf16 v[36:39], v[150:153], v[154:157], v[36:39]
	v_bitop3_b32 v154, v163, v194, v162 bitop3:0x36
	v_bitop3_b32 v155, v165, v194, v162 bitop3:0x36
	v_lshl_add_u32 v154, v154, 4, v164
	s_waitcnt lgkmcnt(0)
	v_mfma_f32_16x16x32_bf16 v[32:35], v[150:153], v[158:161], v[32:35]
	v_bitop3_b32 v158, v163, v195, v162 bitop3:0x36
	v_bitop3_b32 v159, v165, v195, v162 bitop3:0x36
	v_lshl_add_u32 v156, v155, 4, v149
	v_lshl_add_u32 v158, v158, 4, v164
	v_lshl_add_u32 v160, v159, 4, v149
	ds_read_b64_tr_b16 v[154:155], v154
	ds_read_b64_tr_b16 v[156:157], v156
	ds_read_b64_tr_b16 v[158:159], v158
	ds_read_b64_tr_b16 v[160:161], v160
	s_waitcnt lgkmcnt(2)
	v_mfma_f32_16x16x32_bf16 v[28:31], v[150:153], v[154:157], v[28:31]
	v_bitop3_b32 v154, v163, v196, v162 bitop3:0x36
	v_bitop3_b32 v155, v165, v196, v162 bitop3:0x36
	v_lshl_add_u32 v154, v154, 4, v164
	s_waitcnt lgkmcnt(0)
	v_mfma_f32_16x16x32_bf16 v[24:27], v[150:153], v[158:161], v[24:27]
	v_bitop3_b32 v158, v163, v197, v162 bitop3:0x36
	v_lshl_add_u32 v156, v155, 4, v149
	v_lshl_add_u32 v158, v158, 4, v164
	v_bitop3_b32 v159, v165, v197, v162 bitop3:0x36
	ds_read_b64_tr_b16 v[154:155], v154
	ds_read_b64_tr_b16 v[156:157], v156
	v_lshl_add_u32 v149, v159, 4, v149
	ds_read_b64_tr_b16 v[158:159], v158
	ds_read_b64_tr_b16 v[160:161], v149
	s_waitcnt lgkmcnt(2)
	v_mfma_f32_16x16x32_bf16 v[20:23], v[150:153], v[154:157], v[20:23]
	s_waitcnt lgkmcnt(0)
	s_add_u32 s52, s52, 0x20000
	s_waitcnt lgkmcnt(0)
	v_mfma_f32_16x16x32_bf16 v[16:19], v[150:153], v[158:161], v[16:19]
	s_addc_u32 s53, s53, 0
	s_cmp_eq_u32 s52, 0x80000
	v_add_u32_e32 v148, 64, v148
	s_cbranch_scc1 .LBB0_1609
	s_branch .LBB0_1609
